# v24 plus: mLSTM gate-weight table (32 KB f32) staged once per workgroup into unused LDS gaps and read with ds_read_b128 instead of 128 global dwordx4 loads per 4 token rows; same f32 arithmetic
# speedup vs baseline: 1.0070x; 1.0070x over previous
.LBB0_259:
	s_load_dwordx2 s[16:17], s[14:15], 0x90
	s_load_dwordx2 s[18:19], s[14:15], 0x10
	s_ashr_i32 s47, s1, 6
	s_lshl_b32 s0, s0, 3
	v_and_b32_e32 v189, 63, v188
	s_add_i32 s45, s0, s47
	s_cmpk_gt_i32 s45, 0x1fff
	v_lshlrev_b32_e32 v128, 3, v189
	s_cbranch_scc1 .LBB0_290
	v_lshlrev_b32_e32 v0, 2, v189
	v_mov_b32_e32 v129, 0
	v_xor_b32_e32 v190, 4, v0
	v_xor_b32_e32 v191, 8, v0
	v_xor_b32_e32 v192, 16, v0
	v_xor_b32_e32 v193, 32, v0
	v_xor_b32_e32 v194, 64, v0
	v_xor_b32_e32 v195, 0x80, v0
	s_waitcnt lgkmcnt(0)
	s_add_u32 s68, s16, 0x1e000000
	s_addc_u32 s69, s17, 0
	v_lshlrev_b32_e32 v230, 6, v188
	global_load_dwordx4 v[232:235], v230, s[68:69]
	global_load_dwordx4 v[236:239], v230, s[68:69] offset:16
	global_load_dwordx4 v[240:243], v230, s[68:69] offset:32
	global_load_dwordx4 v[244:247], v230, s[68:69] offset:48
	v_lshrrev_b32_e32 v231, 7, v188
	v_lshlrev_b32_e32 v231, 15, v231
	v_and_b32_e32 v248, 1, v188
	v_lshl_or_b32 v231, v248, 14, v231
	v_bfe_u32 v248, v188, 1, 6
	v_lshl_add_u32 v231, v248, 4, v231
	v_add_u32_e32 v231, 0x2100, v231
	s_waitcnt vmcnt(0)
	ds_write_b128 v231, v[232:235]
	ds_write_b128 v231, v[236:239] offset:1024
	ds_write_b128 v231, v[240:243] offset:2048
	ds_write_b128 v231, v[244:247] offset:3072
	s_waitcnt lgkmcnt(0)
	s_barrier
	v_lshlrev_b32_e32 v230, 4, v189
	v_add_u32_e32 v230, 0x2100, v230
	v_add_u32_e32 v231, 0x10000, v230
	v_lshl_add_u64 v[130:131], s[16:17], 0, v[128:129]
	s_mov_b64 s[10:11], 0xd800000
	v_lshlrev_b32_e32 v0, 4, v189
	v_mov_b32_e32 v1, v129
	v_lshl_add_u64 v[132:133], v[130:131], 0, s[10:11]
	v_lshl_add_u64 v[2:3], s[18:19], 0, v[0:1]
	s_mov_b64 s[10:11], 0x1000
	v_lshl_add_u64 v[134:135], v[2:3], 0, s[10:11]
	s_mov_b64 s[10:11], 0x5800000
	v_lshlrev_b32_e32 v4, 7, v189
	v_mov_b32_e32 v5, v129
	s_load_dwordx2 s[20:21], s[14:15], 0x40
	s_load_dwordx2 s[0:1], s[14:15], 0x0
	v_lshl_add_u64 v[136:137], v[130:131], 0, s[10:11]
	v_lshl_add_u64 v[4:5], s[16:17], 0, v[4:5]
	s_mov_b64 s[10:11], 0x1e000000
	s_add_u32 s49, s16, 0x5740000
	v_lshl_add_u64 v[138:139], v[4:5], 0, s[10:11]
	s_mov_b64 s[10:11], 0x2000
	s_addc_u32 s51, s17, 0
	v_lshl_add_u64 v[140:141], v[2:3], 0, s[10:11]
	s_mov_b64 s[10:11], 0x1e002000
	s_add_u32 s53, s16, 0x1d800000
	v_lshl_add_u64 v[142:143], v[4:5], 0, s[10:11]
	s_mov_b64 s[10:11], 0x1e002040
	s_addc_u32 s58, s17, 0
	s_lshl_b32 s22, s45, 2
	s_lshl_b32 s24, s90, 5
	v_lshl_add_u64 v[144:145], v[4:5], 0, s[10:11]
	s_mov_b64 s[10:11], 0x1e004000
	s_waitcnt lgkmcnt(0)
	s_cmp_eq_u64 s[0:1], 0
	v_lshl_add_u64 v[146:147], v[4:5], 0, s[10:11]
	s_mov_b64 s[10:11], 0x1e004040
	s_cselect_b64 s[6:7], -1, 0
	s_cmp_lg_u64 s[0:1], 0
	v_lshl_add_u64 v[148:149], v[4:5], 0, s[10:11]
	s_mov_b64 s[10:11], 0x1e006000
	s_cselect_b64 s[8:9], -1, 0
	v_lshl_add_u64 v[150:151], v[4:5], 0, s[10:11]
	s_mov_b64 s[10:11], 0x1e006040
	s_ashr_i32 s23, s22, 31
	s_ashr_i32 s25, s24, 31
	v_lshl_add_u64 v[152:153], v[4:5], 0, s[10:11]
	s_or_b32 s26, s22, 3
	s_lshl_b64 s[28:29], s[22:23], 11
	s_lshl_b64 s[30:31], s[24:25], 11
	s_lshl_b64 s[10:11], s[22:23], 12
	s_add_u32 s0, s0, s10
	s_addc_u32 s1, s1, s11
	v_lshl_add_u64 v[0:1], s[0:1], 0, v[0:1]
	s_mov_b64 s[0:1], 0x3c00
	v_lshl_add_u64 v[154:155], v[0:1], 0, s[0:1]
	v_cndmask_b32_e64 v0, 0, 1, s[8:9]
	v_cmp_eq_u32_e64 s[4:5], 0, v189
	s_mov_b32 s27, s23
	s_lshl_b64 s[34:35], s[24:25], 12
	s_lshl_b64 s[36:37], s[22:23], 2
	s_lshl_b64 s[38:39], s[24:25], 2
	s_lshl_b64 s[40:41], s[22:23], 5
	s_lshl_b64 s[42:43], s[24:25], 5
	v_cmp_ne_u32_e64 s[8:9], 1, v0
	s_mov_b32 s23, 0xd800000
	v_mov_b32_e32 v196, 0x5740000
	v_mov_b32_e32 v197, 0x358637bd
	s_mov_b32 s59, 0x800000
	s_mov_b32 s60, 0x5800000
	s_mov_b32 s61, 0xf800000
	v_mov_b32_e32 v198, 0x260
	s_mov_b32 s62, 0xbfb8aa3b
	s_mov_b32 s63, 0x3f2aaaab
	s_mov_b32 s44, 0x3ecc95a3
	s_mov_b32 s46, 0x3e9b6dac
	s_mov_b32 s48, 0x3f2aaada
	s_mov_b32 s50, 0x3f317218
	s_mov_b32 s52, 0xb102e308
	s_mov_b32 s64, 0x7f800000
	s_mov_b32 s65, 0x33800000
	v_mov_b32_e32 v199, 0x1d800000
	s_mov_b32 s66, 0x5801000
	v_mov_b32_e32 v200, 0x7f800000
	v_mov_b32_e32 v201, 0x7fc00000
	v_mov_b32_e32 v202, 0xff800000
	s_branch .LBB0_262

.LBB0_270:
	s_or_b64 exec, exec, s[56:57]
	global_load_dwordx4 v[112:115], v[140:141], off
	ds_read_b128 v[116:119], v230 offset:3072
	ds_read_b128 v[120:123], v230 offset:2048
	ds_read_b128 v[124:127], v230 offset:1024
	ds_read_b128 v[204:207], v230
	v_mul_f32_e32 v76, v76, v110
	v_mul_f32_e32 v74, v74, v110
	v_mul_f32_e32 v72, v72, v110
	v_mul_f32_e32 v70, v70, v110
	v_mul_f32_e32 v66, v66, v110
	v_mul_f32_e32 v64, v64, v110
	v_mul_f32_e32 v68, v68, v110
	v_mul_f32_e32 v108, v108, v110
	s_waitcnt vmcnt(0)
	v_mul_f32_e32 v76, v76, v112
	v_mul_f32_e32 v74, v74, v114
	s_waitcnt vmcnt(0)
	s_waitcnt lgkmcnt(1)
	v_pk_fma_f32 v[126:127], v[126:127], v[76:77], 0 op_sel_hi:[1,0,0]
	s_waitcnt vmcnt(0)
	s_waitcnt lgkmcnt(0)
	v_pk_fma_f32 v[78:79], v[206:207], v[76:77], 0 op_sel_hi:[1,0,0]
	v_pk_fma_f32 v[204:205], v[204:205], v[76:77], 0 op_sel_hi:[1,0,0]
	v_pk_fma_f32 v[124:125], v[124:125], v[76:77], 0 op_sel_hi:[1,0,0]
	v_mul_f32_e32 v76, v77, v110
	v_mul_f32_e32 v76, v76, v113
	v_pk_fma_f32 v[112:113], v[122:123], v[76:77], v[78:79] op_sel_hi:[1,0,1]
	v_pk_fma_f32 v[204:205], v[120:121], v[76:77], v[204:205] op_sel_hi:[1,0,1]
	v_pk_fma_f32 v[206:207], v[76:77], v[118:119], v[126:127] op_sel_hi:[0,1,1]
	v_pk_fma_f32 v[208:209], v[76:77], v[116:117], v[124:125] op_sel_hi:[0,1,1]
	ds_read_b128 v[76:79], v230 offset:19456
	ds_read_b128 v[116:119], v230 offset:18432
	ds_read_b128 v[120:123], v230 offset:17408
	ds_read_b128 v[124:127], v230 offset:16384
	s_waitcnt vmcnt(0)
	s_waitcnt lgkmcnt(1)
	v_pk_fma_f32 v[120:121], v[74:75], v[120:121], v[208:209] op_sel_hi:[0,1,1]
	s_waitcnt vmcnt(0)
	s_waitcnt lgkmcnt(0)
	v_pk_fma_f32 v[124:125], v[74:75], v[124:125], v[204:205] op_sel_hi:[0,1,1]
	v_pk_fma_f32 v[112:113], v[74:75], v[126:127], v[112:113] op_sel_hi:[0,1,1]
	v_pk_fma_f32 v[122:123], v[74:75], v[122:123], v[206:207] op_sel_hi:[0,1,1]
	v_mul_f32_e32 v74, v75, v110
	v_mul_f32_e32 v74, v74, v115
	v_pk_fma_f32 v[204:205], v[74:75], v[118:119], v[112:113] op_sel_hi:[0,1,1]
	v_pk_fma_f32 v[206:207], v[74:75], v[116:117], v[124:125] op_sel_hi:[0,1,1]
	v_pk_fma_f32 v[78:79], v[74:75], v[78:79], v[122:123] op_sel_hi:[0,1,1]
	v_pk_fma_f32 v[208:209], v[74:75], v[76:77], v[120:121] op_sel_hi:[0,1,1]
	global_load_dwordx4 v[74:77], v[140:141], off offset:1024
	ds_read_b128 v[112:115], v230 offset:35840
	ds_read_b128 v[116:119], v230 offset:34816
	ds_read_b128 v[120:123], v230 offset:33792
	ds_read_b128 v[124:127], v230 offset:32768
	s_waitcnt vmcnt(0)
	v_mul_f32_e32 v72, v72, v74
	v_mul_f32_e32 v70, v70, v76
	s_waitcnt vmcnt(0)
	s_waitcnt lgkmcnt(1)
	v_pk_fma_f32 v[120:121], v[120:121], v[72:73], v[208:209] op_sel_hi:[1,0,1]
	s_waitcnt vmcnt(0)
	s_waitcnt lgkmcnt(0)
	v_pk_fma_f32 v[124:125], v[124:125], v[72:73], v[206:207] op_sel_hi:[1,0,1]
	v_pk_fma_f32 v[126:127], v[126:127], v[72:73], v[204:205] op_sel_hi:[1,0,1]
	v_pk_fma_f32 v[78:79], v[122:123], v[72:73], v[78:79] op_sel_hi:[1,0,1]
	v_mul_f32_e32 v72, v73, v110
	v_mul_f32_e32 v72, v72, v75
	v_pk_fma_f32 v[126:127], v[118:119], v[72:73], v[126:127] op_sel_hi:[1,0,1]
	v_pk_fma_f32 v[124:125], v[116:117], v[72:73], v[124:125] op_sel_hi:[1,0,1]
	v_pk_fma_f32 v[78:79], v[72:73], v[114:115], v[78:79] op_sel_hi:[0,1,1]
	v_pk_fma_f32 v[204:205], v[72:73], v[112:113], v[120:121] op_sel_hi:[0,1,1]
	ds_read_b128 v[72:75], v230 offset:52224
	ds_read_b128 v[112:115], v230 offset:51200
	ds_read_b128 v[116:119], v230 offset:50176
	ds_read_b128 v[120:123], v230 offset:49152
	s_waitcnt vmcnt(0)
	s_waitcnt lgkmcnt(1)
	v_pk_fma_f32 v[116:117], v[70:71], v[116:117], v[204:205] op_sel_hi:[0,1,1]
	s_waitcnt vmcnt(0)
	s_waitcnt lgkmcnt(0)
	v_pk_fma_f32 v[120:121], v[70:71], v[120:121], v[124:125] op_sel_hi:[0,1,1]
	v_pk_fma_f32 v[122:123], v[70:71], v[122:123], v[126:127] op_sel_hi:[0,1,1]
	v_pk_fma_f32 v[78:79], v[70:71], v[118:119], v[78:79] op_sel_hi:[0,1,1]
	v_mul_f32_e32 v70, v71, v110
	v_mul_f32_e32 v70, v70, v77
	v_pk_fma_f32 v[124:125], v[70:71], v[114:115], v[122:123] op_sel_hi:[0,1,1]
	v_pk_fma_f32 v[126:127], v[70:71], v[112:113], v[120:121] op_sel_hi:[0,1,1]
	v_pk_fma_f32 v[78:79], v[70:71], v[74:75], v[78:79] op_sel_hi:[0,1,1]
	v_pk_fma_f32 v[204:205], v[70:71], v[72:73], v[116:117] op_sel_hi:[0,1,1]
	global_load_dwordx4 v[70:73], v[140:141], off offset:2048
	ds_read_b128 v[74:77], v231 offset:3072
	ds_read_b128 v[112:115], v231 offset:2048
	ds_read_b128 v[116:119], v231 offset:1024
	ds_read_b128 v[120:123], v231
	s_waitcnt vmcnt(0)
	v_mul_f32_e32 v66, v66, v70
	v_mul_f32_e32 v64, v64, v72
	s_waitcnt vmcnt(0)
	s_waitcnt lgkmcnt(1)
	v_pk_fma_f32 v[116:117], v[116:117], v[66:67], v[204:205] op_sel_hi:[1,0,1]
	s_waitcnt vmcnt(0)
	s_waitcnt lgkmcnt(0)
	v_pk_fma_f32 v[120:121], v[120:121], v[66:67], v[126:127] op_sel_hi:[1,0,1]
	v_pk_fma_f32 v[122:123], v[122:123], v[66:67], v[124:125] op_sel_hi:[1,0,1]
	v_pk_fma_f32 v[78:79], v[118:119], v[66:67], v[78:79] op_sel_hi:[1,0,1]
	v_mul_f32_e32 v66, v67, v110
	v_mul_f32_e32 v66, v66, v71
	v_pk_fma_f32 v[70:71], v[114:115], v[66:67], v[122:123] op_sel_hi:[1,0,1]
	v_pk_fma_f32 v[124:125], v[112:113], v[66:67], v[120:121] op_sel_hi:[1,0,1]
	v_pk_fma_f32 v[78:79], v[66:67], v[76:77], v[78:79] op_sel_hi:[0,1,1]
	v_pk_fma_f32 v[66:67], v[66:67], v[74:75], v[116:117] op_sel_hi:[0,1,1]
	ds_read_b128 v[74:77], v231 offset:19456
	ds_read_b128 v[112:115], v231 offset:18432
	ds_read_b128 v[116:119], v231 offset:17408
	ds_read_b128 v[120:123], v231 offset:16384
	s_waitcnt vmcnt(0)
	s_waitcnt lgkmcnt(1)
	v_pk_fma_f32 v[66:67], v[64:65], v[116:117], v[66:67] op_sel_hi:[0,1,1]
	s_waitcnt vmcnt(0)
	s_waitcnt lgkmcnt(0)
	v_pk_fma_f32 v[120:121], v[64:65], v[120:121], v[124:125] op_sel_hi:[0,1,1]
	v_pk_fma_f32 v[70:71], v[64:65], v[122:123], v[70:71] op_sel_hi:[0,1,1]
	v_pk_fma_f32 v[78:79], v[64:65], v[118:119], v[78:79] op_sel_hi:[0,1,1]
	v_mul_f32_e32 v64, v65, v110
	v_mul_f32_e32 v64, v64, v73
	v_pk_fma_f32 v[122:123], v[64:65], v[114:115], v[70:71] op_sel_hi:[0,1,1]
	v_pk_fma_f32 v[120:121], v[64:65], v[112:113], v[120:121] op_sel_hi:[0,1,1]
	v_pk_fma_f32 v[78:79], v[64:65], v[76:77], v[78:79] op_sel_hi:[0,1,1]
	v_pk_fma_f32 v[124:125], v[64:65], v[74:75], v[66:67] op_sel_hi:[0,1,1]
	global_load_dwordx4 v[64:67], v[140:141], off offset:3072
	ds_read_b128 v[70:73], v231 offset:35840
	ds_read_b128 v[74:77], v231 offset:34816
	ds_read_b128 v[112:115], v231 offset:33792
	ds_read_b128 v[116:119], v231 offset:32768
	s_waitcnt vmcnt(0)
	v_mul_f32_e32 v64, v68, v64
	v_mul_f32_e32 v66, v108, v66
	s_waitcnt vmcnt(0)
	s_waitcnt lgkmcnt(1)
	v_pk_fma_f32 v[112:113], v[112:113], v[64:65], v[124:125] op_sel_hi:[1,0,1]
	s_waitcnt vmcnt(0)
	s_waitcnt lgkmcnt(0)
	v_pk_fma_f32 v[116:117], v[116:117], v[64:65], v[120:121] op_sel_hi:[1,0,1]
	v_pk_fma_f32 v[118:119], v[118:119], v[64:65], v[122:123] op_sel_hi:[1,0,1]
	v_pk_fma_f32 v[78:79], v[114:115], v[64:65], v[78:79] op_sel_hi:[1,0,1]
	v_mul_f32_e32 v64, v69, v110
	v_mul_f32_e32 v68, v64, v65
	v_pk_fma_f32 v[114:115], v[76:77], v[68:69], v[118:119] op_sel_hi:[1,0,1]
	v_pk_fma_f32 v[116:117], v[74:75], v[68:69], v[116:117] op_sel_hi:[1,0,1]
	v_pk_fma_f32 v[64:65], v[68:69], v[72:73], v[78:79] op_sel_hi:[0,1,1]
	v_pk_fma_f32 v[112:113], v[68:69], v[70:71], v[112:113] op_sel_hi:[0,1,1]
	ds_read_b128 v[68:71], v231 offset:52224
	ds_read_b128 v[72:75], v231 offset:51200
	ds_read_b128 v[76:79], v231 offset:50176
	ds_read_b128 v[118:121], v231 offset:49152
	s_waitcnt vmcnt(0)
	s_waitcnt lgkmcnt(1)
	v_pk_fma_f32 v[76:77], v[66:67], v[76:77], v[112:113] op_sel_hi:[0,1,1]
	s_waitcnt vmcnt(0)
	s_waitcnt lgkmcnt(0)
	v_pk_fma_f32 v[116:117], v[66:67], v[118:119], v[116:117] op_sel_hi:[0,1,1]
	v_pk_fma_f32 v[114:115], v[66:67], v[120:121], v[114:115] op_sel_hi:[0,1,1]
	v_pk_fma_f32 v[64:65], v[66:67], v[78:79], v[64:65] op_sel_hi:[0,1,1]
	v_mul_f32_e32 v66, v109, v110
	v_mul_f32_e32 v78, v66, v67
	v_pk_fma_f32 v[64:65], v[78:79], v[70:71], v[64:65] op_sel_hi:[0,1,1]
	v_pk_fma_f32 v[70:71], v[78:79], v[68:69], v[76:77] op_sel_hi:[0,1,1]
	ds_bpermute_b32 v77, v190, v64
	ds_bpermute_b32 v68, v190, v70
	v_pk_fma_f32 v[66:67], v[78:79], v[74:75], v[114:115] op_sel_hi:[0,1,1]
	v_pk_fma_f32 v[72:73], v[78:79], v[72:73], v[116:117] op_sel_hi:[0,1,1]
	ds_bpermute_b32 v74, v190, v72
	s_waitcnt lgkmcnt(2)
	v_add_f32_e32 v64, v64, v77
	ds_bpermute_b32 v77, v191, v64
	s_waitcnt lgkmcnt(2)
	v_add_f32_e32 v68, v70, v68
	ds_bpermute_b32 v75, v190, v73
	ds_bpermute_b32 v70, v190, v71
	ds_bpermute_b32 v76, v190, v66
	s_waitcnt lgkmcnt(3)
	v_add_f32_e32 v64, v64, v77
	ds_bpermute_b32 v77, v192, v64
	s_waitcnt lgkmcnt(3)
	v_pk_add_f32 v[72:73], v[72:73], v[74:75]
	s_waitcnt lgkmcnt(2)
	v_add_f32_e32 v70, v71, v70
	ds_bpermute_b32 v69, v191, v68
	ds_bpermute_b32 v74, v191, v72
	s_waitcnt lgkmcnt(2)
	v_add_f32_e32 v64, v64, v77
	ds_bpermute_b32 v77, v193, v64
	ds_bpermute_b32 v75, v191, v73
	ds_bpermute_b32 v71, v191, v70
	s_waitcnt lgkmcnt(4)
	v_add_f32_e32 v68, v68, v69
	ds_bpermute_b32 v69, v192, v68
	s_waitcnt lgkmcnt(3)
	v_add_f32_e32 v64, v64, v77
	ds_bpermute_b32 v77, v194, v64
	s_waitcnt lgkmcnt(3)
	v_pk_add_f32 v[72:73], v[72:73], v[74:75]
	s_waitcnt lgkmcnt(2)
	v_add_f32_e32 v70, v70, v71
	ds_bpermute_b32 v74, v192, v72
	ds_bpermute_b32 v75, v192, v73
	s_waitcnt lgkmcnt(2)
	v_add_f32_e32 v108, v64, v77
	ds_bpermute_b32 v77, v190, v67
	ds_bpermute_b32 v64, v190, v65
	ds_bpermute_b32 v71, v192, v70
	v_add_f32_e32 v68, v68, v69
	s_waitcnt lgkmcnt(3)
	v_pk_add_f32 v[72:73], v[72:73], v[74:75]
	s_waitcnt lgkmcnt(2)
	v_pk_add_f32 v[66:67], v[66:67], v[76:77]
	s_waitcnt lgkmcnt(1)
	v_add_f32_e32 v64, v65, v64
	ds_bpermute_b32 v76, v191, v66
	ds_bpermute_b32 v77, v191, v67
	ds_bpermute_b32 v65, v191, v64
	s_waitcnt lgkmcnt(3)
	v_add_f32_e32 v70, v70, v71
	ds_bpermute_b32 v69, v193, v68
	ds_bpermute_b32 v74, v193, v72
	s_waitcnt lgkmcnt(3)
	v_pk_add_f32 v[66:67], v[66:67], v[76:77]
	s_waitcnt lgkmcnt(2)
	v_add_f32_e32 v64, v64, v65
	ds_bpermute_b32 v76, v192, v66
	ds_bpermute_b32 v77, v192, v67
	ds_bpermute_b32 v65, v192, v64
	ds_bpermute_b32 v75, v193, v73
	ds_bpermute_b32 v71, v193, v70
	s_waitcnt lgkmcnt(6)
	v_add_f32_e32 v68, v68, v69
	s_waitcnt lgkmcnt(3)
	v_pk_add_f32 v[66:67], v[66:67], v[76:77]
	s_waitcnt lgkmcnt(2)
	v_add_f32_e32 v64, v64, v65
	ds_bpermute_b32 v76, v193, v66
	ds_bpermute_b32 v77, v193, v67
	ds_bpermute_b32 v65, v193, v64
	s_waitcnt lgkmcnt(4)
	v_pk_add_f32 v[72:73], v[72:73], v[74:75]
	s_waitcnt lgkmcnt(3)
	v_add_f32_e32 v70, v70, v71
	ds_bpermute_b32 v69, v194, v68
	s_waitcnt lgkmcnt(2)
	v_pk_add_f32 v[66:67], v[66:67], v[76:77]
	s_waitcnt lgkmcnt(1)
	v_add_f32_e32 v64, v64, v65
	ds_bpermute_b32 v74, v194, v72
	ds_bpermute_b32 v75, v194, v73
	ds_bpermute_b32 v71, v194, v70
	ds_bpermute_b32 v76, v194, v66
	ds_bpermute_b32 v77, v194, v67
	ds_bpermute_b32 v65, v194, v64
	s_waitcnt lgkmcnt(6)
	v_add_f32_e32 v68, v68, v69
	s_waitcnt lgkmcnt(4)
	v_pk_add_f32 v[72:73], v[72:73], v[74:75]
	s_waitcnt lgkmcnt(3)
	v_add_f32_e32 v70, v70, v71
	s_waitcnt lgkmcnt(1)
	v_pk_add_f32 v[76:77], v[66:67], v[76:77]
	s_waitcnt lgkmcnt(0)
	v_add_f32_e32 v110, v64, v65
	ds_bpermute_b32 v69, v195, v68
	ds_bpermute_b32 v74, v195, v72
	ds_bpermute_b32 v75, v195, v73
	ds_bpermute_b32 v71, v195, v70
	ds_bpermute_b32 v109, v195, v108
	ds_bpermute_b32 v78, v195, v76
	ds_bpermute_b32 v79, v195, v77
	ds_bpermute_b32 v111, v195, v110
	s_and_saveexec_b64 s[12:13], s[4:5]
	s_cbranch_execz .LBB0_272
	global_load_dwordx4 v[64:67], v129, s[20:21] offset:16
	s_waitcnt lgkmcnt(0)
	v_add_f32_e32 v203, v110, v111
	v_add_f32_e32 v110, v68, v69
	v_add_f32_e32 v111, v70, v71
	global_load_dwordx4 v[68:71], v129, s[20:21]
	v_add_f32_e32 v224, v108, v109
	v_mov_b64_e32 v[108:109], s[44:45]
	v_pk_add_f32 v[72:73], v[72:73], v[74:75]
	v_pk_add_f32 v[76:77], v[76:77], v[78:79]
	s_add_u32 s56, s16, s40
	s_addc_u32 s57, s17, s41
	s_waitcnt vmcnt(1)
	v_add_f32_e32 v64, v110, v64
	v_mul_f32_e64 v110, |v64|, s62
	v_add_f32_e32 v65, v111, v65
	v_exp_f32_e32 v225, v110
	v_mul_f32_e64 v111, |v65|, s62
	v_exp_f32_e32 v226, v111
	v_add_f32_e32 v66, v224, v66
	v_add_f32_e32 v114, 1.0, v225
	v_frexp_mant_f32_e32 v117, v114
	v_cvt_f64_f32_e32 v[110:111], v114
	v_add_f32_e32 v115, 1.0, v226
	v_frexp_exp_i32_f64_e32 v110, v[110:111]
	v_cmp_gt_f32_e32 vcc, s63, v117
	v_add_f32_e32 v116, -1.0, v114
	v_add_f32_e32 v118, -1.0, v115
	v_frexp_mant_f32_e32 v119, v115
	v_cvt_f64_f32_e32 v[112:113], v115
	v_subbrev_co_u32_e32 v110, vcc, 0, v110, vcc
	v_sub_f32_e32 v120, v116, v114
	v_sub_f32_e32 v111, v118, v115
	v_frexp_exp_i32_f64_e32 v112, v[112:113]
	v_cmp_gt_f32_e32 vcc, s63, v119
	v_sub_f32_e32 v116, v225, v116
	v_sub_f32_e32 v118, v226, v118
	v_add_f32_e32 v113, 1.0, v120
	v_add_f32_e32 v111, 1.0, v111
	v_subbrev_co_u32_e32 v112, vcc, 0, v112, vcc
	v_add_f32_e32 v113, v116, v113
	v_sub_u32_e32 v116, 0, v110
	v_add_f32_e32 v117, v118, v111
	v_sub_u32_e32 v118, 0, v112
	v_cvt_f32_i32_e32 v111, v112
	v_cvt_f32_i32_e32 v110, v110
	v_ldexp_f32 v112, v114, v116
	v_ldexp_f32 v114, v113, v116
	v_ldexp_f32 v113, v115, v118
	v_ldexp_f32 v115, v117, v118
	v_pk_add_f32 v[116:117], v[112:113], 1.0 op_sel_hi:[1,0]
	v_pk_add_f32 v[118:119], v[112:113], -1.0 op_sel_hi:[1,0]
	v_pk_add_f32 v[120:121], v[116:117], -1.0 op_sel_hi:[1,0]
	v_pk_add_f32 v[122:123], v[118:119], 1.0 op_sel_hi:[1,0]
	v_pk_add_f32 v[120:121], v[112:113], v[120:121] neg_lo:[0,1] neg_hi:[0,1]
	v_pk_add_f32 v[112:113], v[112:113], v[122:123] neg_lo:[0,1] neg_hi:[0,1]
	v_pk_mul_f32 v[122:123], v[110:111], s[50:51] op_sel_hi:[1,0]
	v_pk_add_f32 v[120:121], v[114:115], v[120:121]
	v_pk_add_f32 v[112:113], v[114:115], v[112:113]
	v_pk_fma_f32 v[114:115], v[110:111], s[50:51], v[122:123] op_sel_hi:[1,0,1] neg_lo:[0,0,1] neg_hi:[0,0,1]
	v_pk_add_f32 v[204:205], v[116:117], v[120:121]
	v_pk_fma_f32 v[110:111], v[110:111], s[52:53], v[114:115] op_sel_hi:[1,0,1]
	v_rcp_f32_e32 v114, v204
	v_rcp_f32_e32 v115, v205
	v_pk_add_f32 v[206:207], v[118:119], v[112:113]
	v_pk_add_f32 v[116:117], v[204:205], v[116:117] neg_lo:[0,1] neg_hi:[0,1]
	v_pk_add_f32 v[118:119], v[206:207], v[118:119] neg_lo:[0,1] neg_hi:[0,1]
	v_pk_mul_f32 v[214:215], v[206:207], v[114:115]
	v_pk_add_f32 v[116:117], v[120:121], v[116:117] neg_lo:[0,1] neg_hi:[0,1]
	v_pk_mul_f32 v[216:217], v[204:205], v[214:215]
	v_pk_add_f32 v[112:113], v[112:113], v[118:119] neg_lo:[0,1] neg_hi:[0,1]
	v_pk_fma_f32 v[218:219], v[214:215], v[204:205], v[216:217] neg_lo:[0,0,1] neg_hi:[0,0,1]
	v_pk_add_f32 v[208:209], v[122:123], v[110:111]
	v_pk_fma_f32 v[218:219], v[214:215], v[116:117], v[218:219]
	v_mov_b32_e32 v124, v122
	v_pk_add_f32 v[220:221], v[216:217], v[218:219]
	v_mov_b32_e32 v210, v110
	v_pk_add_f32 v[222:223], v[206:207], v[220:221] neg_lo:[0,1] neg_hi:[0,1]
	v_pk_add_f32 v[216:217], v[220:221], v[216:217] neg_lo:[0,1] neg_hi:[0,1]
	v_pk_add_f32 v[206:207], v[206:207], v[222:223] neg_lo:[0,1] neg_hi:[0,1]
	v_pk_add_f32 v[216:217], v[216:217], v[218:219] neg_lo:[0,1] neg_hi:[0,1]
	v_pk_add_f32 v[206:207], v[206:207], v[220:221] neg_lo:[0,1] neg_hi:[0,1]
	v_mov_b32_e32 v121, v209
	v_pk_add_f32 v[112:113], v[112:113], v[206:207]
	v_mov_b32_e32 v127, v123
	v_pk_add_f32 v[112:113], v[216:217], v[112:113]
	v_mov_b32_e32 v119, v209
	v_pk_add_f32 v[206:207], v[222:223], v[112:113]
	v_mov_b32_e32 v126, v208
	v_pk_mul_f32 v[216:217], v[114:115], v[206:207]
	v_pk_add_f32 v[218:219], v[222:223], v[206:207] neg_lo:[0,1] neg_hi:[0,1]
	v_pk_mul_f32 v[220:221], v[204:205], v[216:217]
	v_pk_add_f32 v[112:113], v[112:113], v[218:219]
	v_pk_add_f32 v[218:219], v[214:215], v[216:217]
	v_pk_fma_f32 v[204:205], v[216:217], v[204:205], v[220:221] neg_lo:[0,0,1] neg_hi:[0,0,1]
	v_pk_add_f32 v[214:215], v[218:219], v[214:215] neg_lo:[0,1] neg_hi:[0,1]
	v_pk_fma_f32 v[116:117], v[216:217], v[116:117], v[204:205]
	v_pk_add_f32 v[204:205], v[216:217], v[214:215] neg_lo:[0,1] neg_hi:[0,1]
	v_pk_add_f32 v[214:215], v[220:221], v[116:117]
	v_mov_b32_e32 v213, v111
	v_pk_add_f32 v[216:217], v[214:215], v[220:221] neg_lo:[0,1] neg_hi:[0,1]
	v_pk_add_f32 v[220:221], v[206:207], v[214:215] neg_lo:[0,1] neg_hi:[0,1]
	v_pk_add_f32 v[116:117], v[216:217], v[116:117] neg_lo:[0,1] neg_hi:[0,1]
	v_pk_add_f32 v[206:207], v[206:207], v[220:221] neg_lo:[0,1] neg_hi:[0,1]
	v_cmp_neq_f32_e32 vcc, s64, v225
	v_pk_add_f32 v[206:207], v[206:207], v[214:215] neg_lo:[0,1] neg_hi:[0,1]
	v_add_f32_e32 v67, v203, v67
	v_pk_add_f32 v[112:113], v[112:113], v[206:207]
	v_mul_f32_e64 v74, |v67|, s62
	v_pk_add_f32 v[112:113], v[116:117], v[112:113]
	v_exp_f32_e32 v203, v74
	v_pk_add_f32 v[112:113], v[220:221], v[112:113]
	v_min_f32_e32 v64, 0, v64
	v_pk_mul_f32 v[112:113], v[114:115], v[112:113]
	v_min_f32_e32 v65, 0, v65
	v_pk_add_f32 v[112:113], v[204:205], v[112:113]
	v_add_f32_e32 v74, 1.0, v203
	v_pk_add_f32 v[114:115], v[218:219], v[112:113]
	s_waitcnt vmcnt(0)
	v_pk_add_f32 v[68:69], v[72:73], v[68:69]
	v_pk_add_f32 v[116:117], v[114:115], v[218:219] neg_lo:[0,1] neg_hi:[0,1]
	v_pk_mul_f32 v[206:207], v[114:115], v[114:115]
	v_pk_add_f32 v[112:113], v[112:113], v[116:117] neg_lo:[0,1] neg_hi:[0,1]
	v_pk_fma_f32 v[116:117], v[206:207], s[46:47], v[108:109] op_sel_hi:[1,0,0]
	v_ldexp_f32 v204, v114, 1
	v_ldexp_f32 v205, v115, 1
	v_pk_mul_f32 v[114:115], v[114:115], v[206:207]
	v_pk_fma_f32 v[116:117], v[206:207], v[116:117], s[48:49] op_sel_hi:[1,1,0]
	v_ldexp_f32 v211, v113, 1
	v_pk_mul_f32 v[114:115], v[114:115], v[116:117]
	v_ldexp_f32 v112, v112, 1
	v_pk_add_f32 v[116:117], v[204:205], v[114:115]
	v_mov_b32_e32 v113, v211
	v_pk_add_f32 v[204:205], v[116:117], v[204:205] neg_lo:[0,1] neg_hi:[0,1]
	v_mov_b32_e32 v120, v116
	v_pk_add_f32 v[114:115], v[114:115], v[204:205] neg_lo:[0,1] neg_hi:[0,1]
	v_add_f32_e32 v72, -1.0, v74
	v_pk_add_f32 v[204:205], v[112:113], v[114:115]
	v_mov_b32_e32 v125, v115
	v_mov_b32_e32 v115, v117
	v_mov_b32_e32 v113, v205
	v_pk_add_f32 v[206:207], v[116:117], v[204:205]
	v_pk_add_f32 v[112:113], v[112:113], v[114:115]
	v_pk_add_f32 v[114:115], v[208:209], v[206:207]
	v_pk_add_f32 v[124:125], v[124:125], v[210:211]
	v_mov_b32_e32 v210, v206
	v_mov_b32_e32 v211, v115
	v_pk_add_f32 v[120:121], v[210:211], v[120:121] neg_lo:[0,1] neg_hi:[0,1]
	v_mov_b32_e32 v118, v114
	v_mov_b32_e32 v210, v208
	v_mov_b32_e32 v123, v121
	v_mov_b32_e32 v212, v206
	v_pk_add_f32 v[118:119], v[118:119], v[126:127] neg_lo:[0,1] neg_hi:[0,1]
	v_pk_add_f32 v[122:123], v[210:211], v[122:123] neg_lo:[0,1] neg_hi:[0,1]
	v_pk_add_f32 v[126:127], v[212:213], v[118:119] neg_lo:[0,1] neg_hi:[0,1]
	v_mov_b32_e32 v210, v122
	v_mov_b32_e32 v211, v119
	v_mov_b32_e32 v212, v114
	v_mov_b32_e32 v213, v207
	v_mov_b32_e32 v119, v117
	v_pk_add_f32 v[210:211], v[110:111], v[210:211] neg_lo:[0,1] neg_hi:[0,1]
	v_pk_add_f32 v[118:119], v[212:213], v[118:119] neg_lo:[0,1] neg_hi:[0,1]
	v_mov_b32_e32 v111, v209
	v_pk_add_f32 v[118:119], v[124:125], v[118:119] neg_lo:[0,1] neg_hi:[0,1]
	v_pk_add_f32 v[110:111], v[110:111], v[122:123] neg_lo:[0,1] neg_hi:[0,1]
	v_pk_add_f32 v[112:113], v[112:113], v[120:121] neg_lo:[0,1] neg_hi:[0,1]
	v_pk_add_f32 v[122:123], v[126:127], v[118:119]
	v_pk_add_f32 v[120:121], v[112:113], v[110:111]
	v_mov_b32_e32 v111, v127
	v_mov_b32_e32 v113, v119
	v_pk_add_f32 v[112:113], v[110:111], v[112:113]
	v_pk_add_f32 v[116:117], v[206:207], v[116:117] neg_lo:[0,1] neg_hi:[0,1]
	v_pk_add_f32 v[112:113], v[112:113], v[210:211] neg_lo:[0,1] neg_hi:[0,1]
	v_mov_b32_e32 v118, v120
	v_mov_b32_e32 v119, v123
	v_pk_add_f32 v[116:117], v[204:205], v[116:117] neg_lo:[0,1] neg_hi:[0,1]
	v_pk_add_f32 v[118:119], v[118:119], v[112:113] neg_lo:[0,1] neg_hi:[0,1]
	v_pk_add_f32 v[112:113], v[116:117], v[112:113] neg_lo:[0,1] neg_hi:[0,1]
	v_pk_add_f32 v[110:111], v[110:111], v[118:119] neg_lo:[0,1] neg_hi:[0,1]
	v_sub_f32_e32 v73, v72, v74
	v_pk_add_f32 v[110:111], v[112:113], v[110:111]
	v_pk_add_f32 v[112:113], v[122:123], v[120:121]
	v_add_f32_e32 v73, 1.0, v73
	v_pk_add_f32 v[116:117], v[114:115], v[112:113]
	v_sub_f32_e32 v72, v203, v72
	v_pk_add_f32 v[114:115], v[116:117], v[114:115] neg_lo:[0,1] neg_hi:[0,1]
	v_pk_add_f32 v[70:71], v[76:77], v[70:71]
	v_pk_add_f32 v[112:113], v[112:113], v[114:115] neg_lo:[0,1] neg_hi:[0,1]
	v_add_f32_e32 v75, v72, v73
	v_pk_add_f32 v[110:111], v[110:111], v[112:113]
	v_mul_f32_e64 v112, |v66|, s62
	v_pk_add_f32 v[110:111], v[116:117], v[110:111]
	v_exp_f32_e32 v204, v112
	v_cndmask_b32_e32 v110, v200, v110, vcc
	v_cmp_neq_f32_e32 vcc, s64, v226
	v_frexp_mant_f32_e32 v76, v74
	v_add_f32_e32 v112, 1.0, v204
	v_cndmask_b32_e32 v111, v200, v111, vcc
	v_cmp_ngt_f32_e32 vcc, -1.0, v226
	v_frexp_mant_f32_e32 v114, v112
	v_cvt_f64_f32_e32 v[72:73], v74
	v_cndmask_b32_e32 v111, v201, v111, vcc
	v_cmp_ngt_f32_e32 vcc, -1.0, v225
	v_frexp_exp_i32_f64_e32 v72, v[72:73]
	v_min_f32_e32 v66, 0, v66
	v_cndmask_b32_e32 v110, v201, v110, vcc
	v_cmp_neq_f32_e32 vcc, -1.0, v225
	v_min_f32_e32 v67, 0, v67
	s_nop 0
	v_cndmask_b32_e32 v110, v202, v110, vcc
	v_cmp_neq_f32_e32 vcc, -1.0, v226
	s_nop 1
	v_cndmask_b32_e32 v111, v202, v111, vcc
	v_cmp_lt_f32_e64 vcc, |v226|, s65
	s_nop 1
	v_cndmask_b32_e32 v111, v111, v226, vcc
	v_cmp_lt_f32_e64 vcc, |v225|, s65
	s_nop 1
	v_cndmask_b32_e32 v110, v110, v225, vcc
	v_pk_add_f32 v[64:65], v[64:65], v[110:111] neg_lo:[0,1] neg_hi:[0,1]
	v_add_f32_e32 v110, -1.0, v112
	v_sub_f32_e32 v111, v110, v112
	v_add_f32_e32 v111, 1.0, v111
	v_sub_f32_e32 v110, v204, v110
	v_add_f32_e32 v113, v110, v111
	v_cvt_f64_f32_e32 v[110:111], v112
	v_frexp_exp_i32_f64_e32 v110, v[110:111]
	v_cmp_gt_f32_e32 vcc, s63, v114
	s_nop 1
	v_subbrev_co_u32_e32 v122, vcc, 0, v110, vcc
	v_cmp_gt_f32_e32 vcc, s63, v76
	v_sub_u32_e32 v111, 0, v122
	v_ldexp_f32 v110, v112, v111
	v_subbrev_co_u32_e32 v123, vcc, 0, v72, vcc
	v_sub_u32_e32 v72, 0, v123
	v_ldexp_f32 v112, v113, v111
	v_ldexp_f32 v111, v74, v72
	v_ldexp_f32 v113, v75, v72
	v_pk_add_f32 v[72:73], v[110:111], 1.0 op_sel_hi:[1,0]
	v_pk_add_f32 v[114:115], v[110:111], -1.0 op_sel_hi:[1,0]
	v_pk_add_f32 v[74:75], v[72:73], -1.0 op_sel_hi:[1,0]
	v_pk_add_f32 v[116:117], v[114:115], 1.0 op_sel_hi:[1,0]
	v_pk_add_f32 v[74:75], v[110:111], v[74:75] neg_lo:[0,1] neg_hi:[0,1]
	v_pk_add_f32 v[110:111], v[110:111], v[116:117] neg_lo:[0,1] neg_hi:[0,1]
	v_pk_add_f32 v[74:75], v[112:113], v[74:75]
	v_pk_add_f32 v[110:111], v[112:113], v[110:111]
	v_pk_add_f32 v[76:77], v[72:73], v[74:75]
	v_pk_add_f32 v[112:113], v[114:115], v[110:111]
	v_rcp_f32_e32 v78, v76
	v_rcp_f32_e32 v79, v77
	v_pk_add_f32 v[72:73], v[76:77], v[72:73] neg_lo:[0,1] neg_hi:[0,1]
	v_pk_add_f32 v[114:115], v[112:113], v[114:115] neg_lo:[0,1] neg_hi:[0,1]
	v_pk_add_f32 v[72:73], v[74:75], v[72:73] neg_lo:[0,1] neg_hi:[0,1]
	v_pk_mul_f32 v[74:75], v[112:113], v[78:79]
	v_pk_add_f32 v[110:111], v[110:111], v[114:115] neg_lo:[0,1] neg_hi:[0,1]
	v_pk_mul_f32 v[114:115], v[76:77], v[74:75]
	v_cmp_neq_f32_e32 vcc, s64, v204
	v_pk_fma_f32 v[116:117], v[74:75], v[76:77], v[114:115] neg_lo:[0,0,1] neg_hi:[0,0,1]
	s_nop 0
	v_pk_fma_f32 v[116:117], v[74:75], v[72:73], v[116:117]
	s_nop 0
	v_pk_add_f32 v[118:119], v[114:115], v[116:117]
	s_nop 0
	v_pk_add_f32 v[120:121], v[112:113], v[118:119] neg_lo:[0,1] neg_hi:[0,1]
	v_pk_add_f32 v[114:115], v[118:119], v[114:115] neg_lo:[0,1] neg_hi:[0,1]
	v_pk_add_f32 v[112:113], v[112:113], v[120:121] neg_lo:[0,1] neg_hi:[0,1]
	s_nop 0
	v_pk_add_f32 v[112:113], v[112:113], v[118:119] neg_lo:[0,1] neg_hi:[0,1]
	s_nop 0
	v_pk_add_f32 v[110:111], v[110:111], v[112:113]
	v_pk_add_f32 v[112:113], v[114:115], v[116:117] neg_lo:[0,1] neg_hi:[0,1]
	s_nop 0
	v_pk_add_f32 v[110:111], v[112:113], v[110:111]
	s_nop 0
	v_pk_add_f32 v[112:113], v[120:121], v[110:111]
	s_nop 0
	v_pk_mul_f32 v[114:115], v[78:79], v[112:113]
	s_nop 0
	v_pk_mul_f32 v[116:117], v[76:77], v[114:115]
	s_nop 0
	v_pk_fma_f32 v[76:77], v[114:115], v[76:77], v[116:117] neg_lo:[0,0,1] neg_hi:[0,0,1]
	s_nop 0
	v_pk_fma_f32 v[72:73], v[114:115], v[72:73], v[76:77]
	v_pk_add_f32 v[76:77], v[120:121], v[112:113] neg_lo:[0,1] neg_hi:[0,1]
	s_nop 0
	v_pk_add_f32 v[76:77], v[110:111], v[76:77]
	v_pk_add_f32 v[110:111], v[116:117], v[72:73]
	s_nop 0
	v_pk_add_f32 v[118:119], v[112:113], v[110:111] neg_lo:[0,1] neg_hi:[0,1]
	v_pk_add_f32 v[116:117], v[110:111], v[116:117] neg_lo:[0,1] neg_hi:[0,1]
	v_pk_add_f32 v[112:113], v[112:113], v[118:119] neg_lo:[0,1] neg_hi:[0,1]
	v_pk_add_f32 v[72:73], v[116:117], v[72:73] neg_lo:[0,1] neg_hi:[0,1]
	v_pk_add_f32 v[110:111], v[112:113], v[110:111] neg_lo:[0,1] neg_hi:[0,1]
	s_nop 0
	v_pk_add_f32 v[76:77], v[76:77], v[110:111]
	v_cvt_f32_i32_e32 v111, v123
	v_pk_add_f32 v[72:73], v[72:73], v[76:77]
	v_pk_add_f32 v[76:77], v[74:75], v[114:115]
	v_pk_add_f32 v[72:73], v[118:119], v[72:73]
	v_pk_add_f32 v[74:75], v[76:77], v[74:75] neg_lo:[0,1] neg_hi:[0,1]
	v_pk_mul_f32 v[72:73], v[78:79], v[72:73]
	v_pk_add_f32 v[74:75], v[114:115], v[74:75] neg_lo:[0,1] neg_hi:[0,1]
	v_cvt_f32_i32_e32 v110, v122
	v_pk_add_f32 v[72:73], v[74:75], v[72:73]
	s_nop 0
	v_pk_add_f32 v[74:75], v[76:77], v[72:73]
	s_nop 0
	v_pk_mul_f32 v[78:79], v[74:75], v[74:75]
	v_pk_add_f32 v[76:77], v[74:75], v[76:77] neg_lo:[0,1] neg_hi:[0,1]
	v_pk_fma_f32 v[108:109], v[78:79], s[46:47], v[108:109] op_sel_hi:[1,0,0]
	v_pk_add_f32 v[72:73], v[72:73], v[76:77] neg_lo:[0,1] neg_hi:[0,1]
	v_ldexp_f32 v76, v74, 1
	v_pk_fma_f32 v[108:109], v[78:79], v[108:109], s[48:49] op_sel_hi:[1,1,0]
	v_ldexp_f32 v77, v75, 1
	v_pk_mul_f32 v[74:75], v[74:75], v[78:79]
	v_pk_mul_f32 v[78:79], v[110:111], s[50:51] op_sel_hi:[1,0]
	v_pk_mul_f32 v[74:75], v[74:75], v[108:109]
	v_pk_fma_f32 v[114:115], v[110:111], s[50:51], v[78:79] op_sel_hi:[1,0,1] neg_lo:[0,0,1] neg_hi:[0,0,1]
	v_pk_add_f32 v[108:109], v[76:77], v[74:75]
	v_ldexp_f32 v113, v73, 1
	v_pk_add_f32 v[76:77], v[108:109], v[76:77] neg_lo:[0,1] neg_hi:[0,1]
	v_pk_fma_f32 v[110:111], v[110:111], s[52:53], v[114:115] op_sel_hi:[1,0,1]
	v_pk_add_f32 v[74:75], v[74:75], v[76:77] neg_lo:[0,1] neg_hi:[0,1]
	v_ldexp_f32 v72, v72, 1
	v_mov_b32_e32 v76, v78
	v_mov_b32_e32 v77, v75
	v_mov_b32_e32 v112, v110
	v_mov_b32_e32 v73, v113
	v_pk_add_f32 v[76:77], v[76:77], v[112:113]
	v_pk_add_f32 v[112:113], v[72:73], v[74:75]
	v_mov_b32_e32 v75, v109
	v_mov_b32_e32 v73, v113
	v_pk_add_f32 v[114:115], v[78:79], v[110:111]
	v_pk_add_f32 v[72:73], v[72:73], v[74:75]
	v_pk_add_f32 v[74:75], v[108:109], v[112:113]
	v_mov_b32_e32 v124, v108
	v_pk_add_f32 v[116:117], v[114:115], v[74:75]
	v_mov_b32_e32 v122, v74
	v_mov_b32_e32 v123, v117
	v_mov_b32_e32 v125, v115
	v_pk_add_f32 v[122:123], v[122:123], v[124:125] neg_lo:[0,1] neg_hi:[0,1]
	v_mov_b32_e32 v118, v116
	v_mov_b32_e32 v119, v115
	v_mov_b32_e32 v120, v114
	v_mov_b32_e32 v121, v79
	v_mov_b32_e32 v124, v114
	v_mov_b32_e32 v125, v117
	v_mov_b32_e32 v79, v123
	v_pk_add_f32 v[118:119], v[118:119], v[120:121] neg_lo:[0,1] neg_hi:[0,1]
	v_mov_b32_e32 v120, v74
	v_mov_b32_e32 v121, v111
	v_pk_add_f32 v[78:79], v[124:125], v[78:79] neg_lo:[0,1] neg_hi:[0,1]
	v_pk_add_f32 v[120:121], v[120:121], v[118:119] neg_lo:[0,1] neg_hi:[0,1]
	v_mov_b32_e32 v124, v78
	v_mov_b32_e32 v125, v119
	v_mov_b32_e32 v126, v116
	v_mov_b32_e32 v127, v75
	v_mov_b32_e32 v119, v109
	v_pk_add_f32 v[124:125], v[110:111], v[124:125] neg_lo:[0,1] neg_hi:[0,1]
	v_pk_add_f32 v[118:119], v[126:127], v[118:119] neg_lo:[0,1] neg_hi:[0,1]
	v_mov_b32_e32 v111, v115
	v_pk_add_f32 v[76:77], v[76:77], v[118:119] neg_lo:[0,1] neg_hi:[0,1]
	v_pk_add_f32 v[78:79], v[110:111], v[78:79] neg_lo:[0,1] neg_hi:[0,1]
	v_pk_add_f32 v[72:73], v[72:73], v[122:123] neg_lo:[0,1] neg_hi:[0,1]
	v_pk_add_f32 v[74:75], v[74:75], v[108:109] neg_lo:[0,1] neg_hi:[0,1]
	v_pk_add_f32 v[108:109], v[72:73], v[78:79]
	v_mov_b32_e32 v79, v121
	v_mov_b32_e32 v73, v77
	v_pk_add_f32 v[110:111], v[120:121], v[76:77]
	v_pk_add_f32 v[72:73], v[78:79], v[72:73]
	v_mov_b32_e32 v76, v108
	v_pk_add_f32 v[72:73], v[72:73], v[124:125] neg_lo:[0,1] neg_hi:[0,1]
	v_mov_b32_e32 v77, v111
	v_pk_add_f32 v[74:75], v[112:113], v[74:75] neg_lo:[0,1] neg_hi:[0,1]
	v_pk_add_f32 v[76:77], v[76:77], v[72:73] neg_lo:[0,1] neg_hi:[0,1]
	v_pk_add_f32 v[72:73], v[74:75], v[72:73] neg_lo:[0,1] neg_hi:[0,1]
	v_pk_add_f32 v[76:77], v[78:79], v[76:77] neg_lo:[0,1] neg_hi:[0,1]
	v_pk_add_f32 v[74:75], v[110:111], v[108:109]
	v_pk_add_f32 v[72:73], v[72:73], v[76:77]
	v_pk_add_f32 v[76:77], v[116:117], v[74:75]
	s_nop 0
	v_pk_add_f32 v[78:79], v[76:77], v[116:117] neg_lo:[0,1] neg_hi:[0,1]
	s_nop 0
	v_pk_add_f32 v[74:75], v[74:75], v[78:79] neg_lo:[0,1] neg_hi:[0,1]
	s_nop 0
	v_pk_add_f32 v[72:73], v[72:73], v[74:75]
	s_nop 0
	v_pk_add_f32 v[72:73], v[76:77], v[72:73]
	s_nop 0
	v_cndmask_b32_e32 v72, v200, v72, vcc
	v_cmp_neq_f32_e32 vcc, s64, v203
	s_nop 1
	v_cndmask_b32_e32 v73, v200, v73, vcc
	v_cmp_ngt_f32_e32 vcc, -1.0, v203
	s_nop 1
	v_cndmask_b32_e32 v73, v201, v73, vcc
	v_cmp_ngt_f32_e32 vcc, -1.0, v204
	s_nop 1
	v_cndmask_b32_e32 v72, v201, v72, vcc
	v_cmp_neq_f32_e32 vcc, -1.0, v204
	s_nop 1
	v_cndmask_b32_e32 v72, v202, v72, vcc
	v_cmp_neq_f32_e32 vcc, -1.0, v203
	s_nop 1
	v_cndmask_b32_e32 v73, v202, v73, vcc
	v_cmp_lt_f32_e64 vcc, |v203|, s65
	s_nop 1
	v_cndmask_b32_e32 v73, v73, v203, vcc
	v_cmp_lt_f32_e64 vcc, |v204|, s65
	s_nop 1
	v_cndmask_b32_e32 v72, v72, v204, vcc
	v_pk_add_f32 v[66:67], v[66:67], v[72:73] neg_lo:[0,1] neg_hi:[0,1]
	global_store_dwordx4 v199, v[68:71], s[56:57]
	global_store_dwordx4 v199, v[64:67], s[56:57] offset:16

.LBB0_276:
	s_or_b64 exec, exec, s[56:57]
	global_load_dwordx4 v[102:105], v[140:141], off
	ds_read_b128 v[106:109], v230 offset:3072
	ds_read_b128 v[110:113], v230 offset:2048
	ds_read_b128 v[114:117], v230 offset:1024
	ds_read_b128 v[118:121], v230
	v_mul_f32_e32 v76, v76, v100
	v_mul_f32_e32 v74, v74, v100
	v_mul_f32_e32 v72, v72, v100
	v_mul_f32_e32 v70, v70, v100
	v_mul_f32_e32 v66, v66, v100
	v_mul_f32_e32 v64, v64, v100
	v_mul_f32_e32 v68, v68, v100
	v_mul_f32_e32 v98, v98, v100
	s_waitcnt vmcnt(0)
	v_mul_f32_e32 v76, v76, v102
	v_mul_f32_e32 v74, v74, v104
	s_waitcnt vmcnt(0)
	s_waitcnt lgkmcnt(1)
	v_pk_fma_f32 v[116:117], v[116:117], v[76:77], 0 op_sel_hi:[1,0,0]
	s_waitcnt vmcnt(0)
	s_waitcnt lgkmcnt(0)
	v_pk_fma_f32 v[78:79], v[120:121], v[76:77], 0 op_sel_hi:[1,0,0]
	v_pk_fma_f32 v[118:119], v[118:119], v[76:77], 0 op_sel_hi:[1,0,0]
	v_pk_fma_f32 v[114:115], v[114:115], v[76:77], 0 op_sel_hi:[1,0,0]
	v_mul_f32_e32 v76, v77, v100
	v_mul_f32_e32 v76, v76, v103
	v_pk_fma_f32 v[102:103], v[112:113], v[76:77], v[78:79] op_sel_hi:[1,0,1]
	v_pk_fma_f32 v[118:119], v[110:111], v[76:77], v[118:119] op_sel_hi:[1,0,1]
	v_pk_fma_f32 v[120:121], v[76:77], v[108:109], v[116:117] op_sel_hi:[0,1,1]
	v_pk_fma_f32 v[122:123], v[76:77], v[106:107], v[114:115] op_sel_hi:[0,1,1]
	ds_read_b128 v[76:79], v230 offset:19456
	ds_read_b128 v[106:109], v230 offset:18432
	ds_read_b128 v[110:113], v230 offset:17408
	ds_read_b128 v[114:117], v230 offset:16384
	s_waitcnt vmcnt(0)
	s_waitcnt lgkmcnt(1)
	v_pk_fma_f32 v[110:111], v[74:75], v[110:111], v[122:123] op_sel_hi:[0,1,1]
	s_waitcnt vmcnt(0)
	s_waitcnt lgkmcnt(0)
	v_pk_fma_f32 v[114:115], v[74:75], v[114:115], v[118:119] op_sel_hi:[0,1,1]
	v_pk_fma_f32 v[102:103], v[74:75], v[116:117], v[102:103] op_sel_hi:[0,1,1]
	v_pk_fma_f32 v[112:113], v[74:75], v[112:113], v[120:121] op_sel_hi:[0,1,1]
	v_mul_f32_e32 v74, v75, v100
	v_mul_f32_e32 v74, v74, v105
	v_pk_fma_f32 v[118:119], v[74:75], v[108:109], v[102:103] op_sel_hi:[0,1,1]
	v_pk_fma_f32 v[120:121], v[74:75], v[106:107], v[114:115] op_sel_hi:[0,1,1]
	v_pk_fma_f32 v[78:79], v[74:75], v[78:79], v[112:113] op_sel_hi:[0,1,1]
	v_pk_fma_f32 v[122:123], v[74:75], v[76:77], v[110:111] op_sel_hi:[0,1,1]
	global_load_dwordx4 v[74:77], v[140:141], off offset:1024
	ds_read_b128 v[102:105], v230 offset:35840
	ds_read_b128 v[106:109], v230 offset:34816
	ds_read_b128 v[110:113], v230 offset:33792
	ds_read_b128 v[114:117], v230 offset:32768
	s_waitcnt vmcnt(0)
	v_mul_f32_e32 v72, v72, v74
	v_mul_f32_e32 v70, v70, v76
	s_waitcnt vmcnt(0)
	s_waitcnt lgkmcnt(1)
	v_pk_fma_f32 v[110:111], v[110:111], v[72:73], v[122:123] op_sel_hi:[1,0,1]
	s_waitcnt vmcnt(0)
	s_waitcnt lgkmcnt(0)
	v_pk_fma_f32 v[114:115], v[114:115], v[72:73], v[120:121] op_sel_hi:[1,0,1]
	v_pk_fma_f32 v[116:117], v[116:117], v[72:73], v[118:119] op_sel_hi:[1,0,1]
	v_pk_fma_f32 v[78:79], v[112:113], v[72:73], v[78:79] op_sel_hi:[1,0,1]
	v_mul_f32_e32 v72, v73, v100
	v_mul_f32_e32 v72, v72, v75
	v_pk_fma_f32 v[116:117], v[108:109], v[72:73], v[116:117] op_sel_hi:[1,0,1]
	v_pk_fma_f32 v[114:115], v[106:107], v[72:73], v[114:115] op_sel_hi:[1,0,1]
	v_pk_fma_f32 v[78:79], v[72:73], v[104:105], v[78:79] op_sel_hi:[0,1,1]
	v_pk_fma_f32 v[118:119], v[72:73], v[102:103], v[110:111] op_sel_hi:[0,1,1]
	ds_read_b128 v[72:75], v230 offset:52224
	ds_read_b128 v[102:105], v230 offset:51200
	ds_read_b128 v[106:109], v230 offset:50176
	ds_read_b128 v[110:113], v230 offset:49152
	s_waitcnt vmcnt(0)
	s_waitcnt lgkmcnt(1)
	v_pk_fma_f32 v[106:107], v[70:71], v[106:107], v[118:119] op_sel_hi:[0,1,1]
	s_waitcnt vmcnt(0)
	s_waitcnt lgkmcnt(0)
	v_pk_fma_f32 v[110:111], v[70:71], v[110:111], v[114:115] op_sel_hi:[0,1,1]
	v_pk_fma_f32 v[112:113], v[70:71], v[112:113], v[116:117] op_sel_hi:[0,1,1]
	v_pk_fma_f32 v[78:79], v[70:71], v[108:109], v[78:79] op_sel_hi:[0,1,1]
	v_mul_f32_e32 v70, v71, v100
	v_mul_f32_e32 v70, v70, v77
	v_pk_fma_f32 v[114:115], v[70:71], v[104:105], v[112:113] op_sel_hi:[0,1,1]
	v_pk_fma_f32 v[116:117], v[70:71], v[102:103], v[110:111] op_sel_hi:[0,1,1]
	v_pk_fma_f32 v[78:79], v[70:71], v[74:75], v[78:79] op_sel_hi:[0,1,1]
	v_pk_fma_f32 v[118:119], v[70:71], v[72:73], v[106:107] op_sel_hi:[0,1,1]
	global_load_dwordx4 v[70:73], v[140:141], off offset:2048
	ds_read_b128 v[74:77], v231 offset:3072
	ds_read_b128 v[102:105], v231 offset:2048
	ds_read_b128 v[106:109], v231 offset:1024
	ds_read_b128 v[110:113], v231
	s_waitcnt vmcnt(0)
	v_mul_f32_e32 v66, v66, v70
	v_mul_f32_e32 v64, v64, v72
	s_waitcnt vmcnt(0)
	s_waitcnt lgkmcnt(1)
	v_pk_fma_f32 v[106:107], v[106:107], v[66:67], v[118:119] op_sel_hi:[1,0,1]
	s_waitcnt vmcnt(0)
	s_waitcnt lgkmcnt(0)
	v_pk_fma_f32 v[110:111], v[110:111], v[66:67], v[116:117] op_sel_hi:[1,0,1]
	v_pk_fma_f32 v[112:113], v[112:113], v[66:67], v[114:115] op_sel_hi:[1,0,1]
	v_pk_fma_f32 v[78:79], v[108:109], v[66:67], v[78:79] op_sel_hi:[1,0,1]
	v_mul_f32_e32 v66, v67, v100
	v_mul_f32_e32 v66, v66, v71
	v_pk_fma_f32 v[70:71], v[104:105], v[66:67], v[112:113] op_sel_hi:[1,0,1]
	v_pk_fma_f32 v[114:115], v[102:103], v[66:67], v[110:111] op_sel_hi:[1,0,1]
	v_pk_fma_f32 v[78:79], v[66:67], v[76:77], v[78:79] op_sel_hi:[0,1,1]
	v_pk_fma_f32 v[66:67], v[66:67], v[74:75], v[106:107] op_sel_hi:[0,1,1]
	ds_read_b128 v[74:77], v231 offset:19456
	ds_read_b128 v[102:105], v231 offset:18432
	ds_read_b128 v[106:109], v231 offset:17408
	ds_read_b128 v[110:113], v231 offset:16384
	s_waitcnt vmcnt(0)
	s_waitcnt lgkmcnt(1)
	v_pk_fma_f32 v[66:67], v[64:65], v[106:107], v[66:67] op_sel_hi:[0,1,1]
	s_waitcnt vmcnt(0)
	s_waitcnt lgkmcnt(0)
	v_pk_fma_f32 v[110:111], v[64:65], v[110:111], v[114:115] op_sel_hi:[0,1,1]
	v_pk_fma_f32 v[70:71], v[64:65], v[112:113], v[70:71] op_sel_hi:[0,1,1]
	v_pk_fma_f32 v[78:79], v[64:65], v[108:109], v[78:79] op_sel_hi:[0,1,1]
	v_mul_f32_e32 v64, v65, v100
	v_mul_f32_e32 v64, v64, v73
	v_pk_fma_f32 v[112:113], v[64:65], v[104:105], v[70:71] op_sel_hi:[0,1,1]
	v_pk_fma_f32 v[110:111], v[64:65], v[102:103], v[110:111] op_sel_hi:[0,1,1]
	v_pk_fma_f32 v[78:79], v[64:65], v[76:77], v[78:79] op_sel_hi:[0,1,1]
	v_pk_fma_f32 v[114:115], v[64:65], v[74:75], v[66:67] op_sel_hi:[0,1,1]
	global_load_dwordx4 v[64:67], v[140:141], off offset:3072
	ds_read_b128 v[70:73], v231 offset:35840
	ds_read_b128 v[74:77], v231 offset:34816
	ds_read_b128 v[102:105], v231 offset:33792
	ds_read_b128 v[106:109], v231 offset:32768
	s_waitcnt vmcnt(0)
	v_mul_f32_e32 v64, v68, v64
	v_mul_f32_e32 v66, v98, v66
	s_waitcnt vmcnt(0)
	s_waitcnt lgkmcnt(1)
	v_pk_fma_f32 v[102:103], v[102:103], v[64:65], v[114:115] op_sel_hi:[1,0,1]
	s_waitcnt vmcnt(0)
	s_waitcnt lgkmcnt(0)
	v_pk_fma_f32 v[106:107], v[106:107], v[64:65], v[110:111] op_sel_hi:[1,0,1]
	v_pk_fma_f32 v[108:109], v[108:109], v[64:65], v[112:113] op_sel_hi:[1,0,1]
	v_pk_fma_f32 v[78:79], v[104:105], v[64:65], v[78:79] op_sel_hi:[1,0,1]
	v_mul_f32_e32 v64, v69, v100
	v_mul_f32_e32 v68, v64, v65
	v_pk_fma_f32 v[104:105], v[76:77], v[68:69], v[108:109] op_sel_hi:[1,0,1]
	v_pk_fma_f32 v[106:107], v[74:75], v[68:69], v[106:107] op_sel_hi:[1,0,1]
	v_pk_fma_f32 v[64:65], v[68:69], v[72:73], v[78:79] op_sel_hi:[0,1,1]
	v_pk_fma_f32 v[102:103], v[68:69], v[70:71], v[102:103] op_sel_hi:[0,1,1]
	ds_read_b128 v[68:71], v231 offset:52224
	ds_read_b128 v[72:75], v231 offset:51200
	ds_read_b128 v[76:79], v231 offset:50176
	ds_read_b128 v[108:111], v231 offset:49152
	s_waitcnt vmcnt(0)
	s_waitcnt lgkmcnt(1)
	v_pk_fma_f32 v[76:77], v[66:67], v[76:77], v[102:103] op_sel_hi:[0,1,1]
	s_waitcnt vmcnt(0)
	s_waitcnt lgkmcnt(0)
	v_pk_fma_f32 v[106:107], v[66:67], v[108:109], v[106:107] op_sel_hi:[0,1,1]
	v_pk_fma_f32 v[104:105], v[66:67], v[110:111], v[104:105] op_sel_hi:[0,1,1]
	v_pk_fma_f32 v[64:65], v[66:67], v[78:79], v[64:65] op_sel_hi:[0,1,1]
	v_mul_f32_e32 v66, v99, v100
	v_mul_f32_e32 v78, v66, v67
	v_pk_fma_f32 v[64:65], v[78:79], v[70:71], v[64:65] op_sel_hi:[0,1,1]
	v_pk_fma_f32 v[70:71], v[78:79], v[68:69], v[76:77] op_sel_hi:[0,1,1]
	ds_bpermute_b32 v77, v190, v64
	ds_bpermute_b32 v68, v190, v70
	v_pk_fma_f32 v[66:67], v[78:79], v[74:75], v[104:105] op_sel_hi:[0,1,1]
	v_pk_fma_f32 v[72:73], v[78:79], v[72:73], v[106:107] op_sel_hi:[0,1,1]
	ds_bpermute_b32 v74, v190, v72
	s_waitcnt lgkmcnt(2)
	v_add_f32_e32 v64, v64, v77
	ds_bpermute_b32 v77, v191, v64
	s_waitcnt lgkmcnt(2)
	v_add_f32_e32 v68, v70, v68
	ds_bpermute_b32 v75, v190, v73
	ds_bpermute_b32 v70, v190, v71
	ds_bpermute_b32 v76, v190, v66
	s_waitcnt lgkmcnt(3)
	v_add_f32_e32 v64, v64, v77
	ds_bpermute_b32 v77, v192, v64
	s_waitcnt lgkmcnt(3)
	v_pk_add_f32 v[72:73], v[72:73], v[74:75]
	s_waitcnt lgkmcnt(2)
	v_add_f32_e32 v70, v71, v70
	ds_bpermute_b32 v69, v191, v68
	ds_bpermute_b32 v74, v191, v72
	s_waitcnt lgkmcnt(2)
	v_add_f32_e32 v64, v64, v77
	ds_bpermute_b32 v77, v193, v64
	ds_bpermute_b32 v75, v191, v73
	ds_bpermute_b32 v71, v191, v70
	s_waitcnt lgkmcnt(4)
	v_add_f32_e32 v68, v68, v69
	ds_bpermute_b32 v69, v192, v68
	s_waitcnt lgkmcnt(3)
	v_add_f32_e32 v64, v64, v77
	ds_bpermute_b32 v77, v194, v64
	s_waitcnt lgkmcnt(3)
	v_pk_add_f32 v[72:73], v[72:73], v[74:75]
	s_waitcnt lgkmcnt(2)
	v_add_f32_e32 v70, v70, v71
	ds_bpermute_b32 v74, v192, v72
	ds_bpermute_b32 v75, v192, v73
	s_waitcnt lgkmcnt(2)
	v_add_f32_e32 v98, v64, v77
	ds_bpermute_b32 v77, v190, v67
	ds_bpermute_b32 v64, v190, v65
	ds_bpermute_b32 v71, v192, v70
	v_add_f32_e32 v68, v68, v69
	s_waitcnt lgkmcnt(3)
	v_pk_add_f32 v[72:73], v[72:73], v[74:75]
	s_waitcnt lgkmcnt(2)
	v_pk_add_f32 v[66:67], v[66:67], v[76:77]
	s_waitcnt lgkmcnt(1)
	v_add_f32_e32 v64, v65, v64
	ds_bpermute_b32 v76, v191, v66
	ds_bpermute_b32 v77, v191, v67
	ds_bpermute_b32 v65, v191, v64
	s_waitcnt lgkmcnt(3)
	v_add_f32_e32 v70, v70, v71
	ds_bpermute_b32 v69, v193, v68
	ds_bpermute_b32 v74, v193, v72
	s_waitcnt lgkmcnt(3)
	v_pk_add_f32 v[66:67], v[66:67], v[76:77]
	s_waitcnt lgkmcnt(2)
	v_add_f32_e32 v64, v64, v65
	ds_bpermute_b32 v76, v192, v66
	ds_bpermute_b32 v77, v192, v67
	ds_bpermute_b32 v65, v192, v64
	ds_bpermute_b32 v75, v193, v73
	ds_bpermute_b32 v71, v193, v70
	s_waitcnt lgkmcnt(6)
	v_add_f32_e32 v68, v68, v69
	s_waitcnt lgkmcnt(3)
	v_pk_add_f32 v[66:67], v[66:67], v[76:77]
	s_waitcnt lgkmcnt(2)
	v_add_f32_e32 v64, v64, v65
	ds_bpermute_b32 v76, v193, v66
	ds_bpermute_b32 v77, v193, v67
	ds_bpermute_b32 v65, v193, v64
	s_waitcnt lgkmcnt(4)
	v_pk_add_f32 v[72:73], v[72:73], v[74:75]
	s_waitcnt lgkmcnt(3)
	v_add_f32_e32 v70, v70, v71
	ds_bpermute_b32 v69, v194, v68
	s_waitcnt lgkmcnt(2)
	v_pk_add_f32 v[66:67], v[66:67], v[76:77]
	s_waitcnt lgkmcnt(1)
	v_add_f32_e32 v64, v64, v65
	ds_bpermute_b32 v74, v194, v72
	ds_bpermute_b32 v75, v194, v73
	ds_bpermute_b32 v71, v194, v70
	ds_bpermute_b32 v76, v194, v66
	ds_bpermute_b32 v77, v194, v67
	ds_bpermute_b32 v65, v194, v64
	s_waitcnt lgkmcnt(6)
	v_add_f32_e32 v68, v68, v69
	s_waitcnt lgkmcnt(4)
	v_pk_add_f32 v[72:73], v[72:73], v[74:75]
	s_waitcnt lgkmcnt(3)
	v_add_f32_e32 v70, v70, v71
	s_waitcnt lgkmcnt(1)
	v_pk_add_f32 v[76:77], v[66:67], v[76:77]
	s_waitcnt lgkmcnt(0)
	v_add_f32_e32 v100, v64, v65
	ds_bpermute_b32 v69, v195, v68
	ds_bpermute_b32 v74, v195, v72
	ds_bpermute_b32 v75, v195, v73
	ds_bpermute_b32 v71, v195, v70
	ds_bpermute_b32 v99, v195, v98
	ds_bpermute_b32 v78, v195, v76
	ds_bpermute_b32 v79, v195, v77
	ds_bpermute_b32 v101, v195, v100
	s_and_saveexec_b64 s[12:13], s[4:5]
	s_cbranch_execz .LBB0_278
	global_load_dwordx4 v[64:67], v129, s[20:21] offset:16
	s_waitcnt lgkmcnt(0)
	v_add_f32_e32 v203, v100, v101
	v_add_f32_e32 v100, v68, v69
	v_add_f32_e32 v101, v70, v71
	global_load_dwordx4 v[68:71], v129, s[20:21]
	v_add_f32_e32 v214, v98, v99
	v_mov_b64_e32 v[98:99], s[44:45]
	v_pk_add_f32 v[72:73], v[72:73], v[74:75]
	v_pk_add_f32 v[76:77], v[76:77], v[78:79]
	s_add_u32 s56, s16, s40
	s_addc_u32 s57, s17, s41
	s_waitcnt vmcnt(1)
	v_add_f32_e32 v64, v100, v64
	v_mul_f32_e64 v100, |v64|, s62
	v_add_f32_e32 v65, v101, v65
	v_exp_f32_e32 v215, v100
	v_mul_f32_e64 v101, |v65|, s62
	v_exp_f32_e32 v216, v101
	v_add_f32_e32 v66, v214, v66
	v_add_f32_e32 v104, 1.0, v215
	v_frexp_mant_f32_e32 v107, v104
	v_cvt_f64_f32_e32 v[100:101], v104
	v_add_f32_e32 v105, 1.0, v216
	v_frexp_exp_i32_f64_e32 v100, v[100:101]
	v_cmp_gt_f32_e32 vcc, s63, v107
	v_add_f32_e32 v106, -1.0, v104
	v_add_f32_e32 v108, -1.0, v105
	v_frexp_mant_f32_e32 v109, v105
	v_cvt_f64_f32_e32 v[102:103], v105
	v_subbrev_co_u32_e32 v100, vcc, 0, v100, vcc
	v_sub_f32_e32 v110, v106, v104
	v_sub_f32_e32 v101, v108, v105
	v_frexp_exp_i32_f64_e32 v102, v[102:103]
	v_cmp_gt_f32_e32 vcc, s63, v109
	v_sub_f32_e32 v106, v215, v106
	v_sub_f32_e32 v108, v216, v108
	v_add_f32_e32 v103, 1.0, v110
	v_add_f32_e32 v101, 1.0, v101
	v_subbrev_co_u32_e32 v102, vcc, 0, v102, vcc
	v_add_f32_e32 v103, v106, v103
	v_sub_u32_e32 v106, 0, v100
	v_add_f32_e32 v107, v108, v101
	v_sub_u32_e32 v108, 0, v102
	v_cvt_f32_i32_e32 v101, v102
	v_cvt_f32_i32_e32 v100, v100
	v_ldexp_f32 v102, v104, v106
	v_ldexp_f32 v104, v103, v106
	v_ldexp_f32 v103, v105, v108
	v_ldexp_f32 v105, v107, v108
	v_pk_add_f32 v[106:107], v[102:103], 1.0 op_sel_hi:[1,0]
	v_pk_add_f32 v[108:109], v[102:103], -1.0 op_sel_hi:[1,0]
	v_pk_add_f32 v[110:111], v[106:107], -1.0 op_sel_hi:[1,0]
	v_pk_add_f32 v[112:113], v[108:109], 1.0 op_sel_hi:[1,0]
	v_pk_add_f32 v[110:111], v[102:103], v[110:111] neg_lo:[0,1] neg_hi:[0,1]
	v_pk_add_f32 v[102:103], v[102:103], v[112:113] neg_lo:[0,1] neg_hi:[0,1]
	v_pk_mul_f32 v[112:113], v[100:101], s[50:51] op_sel_hi:[1,0]
	v_pk_add_f32 v[110:111], v[104:105], v[110:111]
	v_pk_add_f32 v[102:103], v[104:105], v[102:103]
	v_pk_fma_f32 v[104:105], v[100:101], s[50:51], v[112:113] op_sel_hi:[1,0,1] neg_lo:[0,0,1] neg_hi:[0,0,1]
	v_pk_add_f32 v[118:119], v[106:107], v[110:111]
	v_pk_fma_f32 v[100:101], v[100:101], s[52:53], v[104:105] op_sel_hi:[1,0,1]
	v_rcp_f32_e32 v104, v118
	v_rcp_f32_e32 v105, v119
	v_pk_add_f32 v[120:121], v[108:109], v[102:103]
	v_pk_add_f32 v[106:107], v[118:119], v[106:107] neg_lo:[0,1] neg_hi:[0,1]
	v_pk_add_f32 v[108:109], v[120:121], v[108:109] neg_lo:[0,1] neg_hi:[0,1]
	v_pk_mul_f32 v[204:205], v[120:121], v[104:105]
	v_pk_add_f32 v[106:107], v[110:111], v[106:107] neg_lo:[0,1] neg_hi:[0,1]
	v_pk_mul_f32 v[206:207], v[118:119], v[204:205]
	v_pk_add_f32 v[102:103], v[102:103], v[108:109] neg_lo:[0,1] neg_hi:[0,1]
	v_pk_fma_f32 v[208:209], v[204:205], v[118:119], v[206:207] neg_lo:[0,0,1] neg_hi:[0,0,1]
	v_pk_add_f32 v[122:123], v[112:113], v[100:101]
	v_pk_fma_f32 v[208:209], v[204:205], v[106:107], v[208:209]
	v_mov_b32_e32 v114, v112
	v_pk_add_f32 v[210:211], v[206:207], v[208:209]
	v_mov_b32_e32 v124, v100
	v_pk_add_f32 v[212:213], v[120:121], v[210:211] neg_lo:[0,1] neg_hi:[0,1]
	v_pk_add_f32 v[206:207], v[210:211], v[206:207] neg_lo:[0,1] neg_hi:[0,1]
	v_pk_add_f32 v[120:121], v[120:121], v[212:213] neg_lo:[0,1] neg_hi:[0,1]
	v_pk_add_f32 v[206:207], v[206:207], v[208:209] neg_lo:[0,1] neg_hi:[0,1]
	v_pk_add_f32 v[120:121], v[120:121], v[210:211] neg_lo:[0,1] neg_hi:[0,1]
	v_mov_b32_e32 v111, v123
	v_pk_add_f32 v[102:103], v[102:103], v[120:121]
	v_mov_b32_e32 v117, v113
	v_pk_add_f32 v[102:103], v[206:207], v[102:103]
	v_mov_b32_e32 v109, v123
	v_pk_add_f32 v[120:121], v[212:213], v[102:103]
	v_mov_b32_e32 v116, v122
	v_pk_mul_f32 v[206:207], v[104:105], v[120:121]
	v_pk_add_f32 v[208:209], v[212:213], v[120:121] neg_lo:[0,1] neg_hi:[0,1]
	v_pk_mul_f32 v[210:211], v[118:119], v[206:207]
	v_pk_add_f32 v[102:103], v[102:103], v[208:209]
	v_pk_add_f32 v[208:209], v[204:205], v[206:207]
	v_pk_fma_f32 v[118:119], v[206:207], v[118:119], v[210:211] neg_lo:[0,0,1] neg_hi:[0,0,1]
	v_pk_add_f32 v[204:205], v[208:209], v[204:205] neg_lo:[0,1] neg_hi:[0,1]
	v_pk_fma_f32 v[106:107], v[206:207], v[106:107], v[118:119]
	v_pk_add_f32 v[118:119], v[206:207], v[204:205] neg_lo:[0,1] neg_hi:[0,1]
	v_pk_add_f32 v[204:205], v[210:211], v[106:107]
	v_mov_b32_e32 v127, v101
	v_pk_add_f32 v[206:207], v[204:205], v[210:211] neg_lo:[0,1] neg_hi:[0,1]
	v_pk_add_f32 v[210:211], v[120:121], v[204:205] neg_lo:[0,1] neg_hi:[0,1]
	v_pk_add_f32 v[106:107], v[206:207], v[106:107] neg_lo:[0,1] neg_hi:[0,1]
	v_pk_add_f32 v[120:121], v[120:121], v[210:211] neg_lo:[0,1] neg_hi:[0,1]
	v_cmp_neq_f32_e32 vcc, s64, v215
	v_pk_add_f32 v[120:121], v[120:121], v[204:205] neg_lo:[0,1] neg_hi:[0,1]
	v_add_f32_e32 v67, v203, v67
	v_pk_add_f32 v[102:103], v[102:103], v[120:121]
	v_mul_f32_e64 v74, |v67|, s62
	v_pk_add_f32 v[102:103], v[106:107], v[102:103]
	v_min_f32_e32 v64, 0, v64
	v_pk_add_f32 v[102:103], v[210:211], v[102:103]
	v_min_f32_e32 v65, 0, v65
	v_pk_mul_f32 v[102:103], v[104:105], v[102:103]
	s_waitcnt vmcnt(0)
	v_pk_add_f32 v[68:69], v[72:73], v[68:69]
	v_pk_add_f32 v[102:103], v[118:119], v[102:103]
	v_pk_add_f32 v[70:71], v[76:77], v[70:71]
	v_pk_add_f32 v[104:105], v[208:209], v[102:103]
	v_min_f32_e32 v67, 0, v67
	v_pk_add_f32 v[106:107], v[104:105], v[208:209] neg_lo:[0,1] neg_hi:[0,1]
	v_pk_mul_f32 v[120:121], v[104:105], v[104:105]
	v_pk_add_f32 v[102:103], v[102:103], v[106:107] neg_lo:[0,1] neg_hi:[0,1]
	v_pk_fma_f32 v[106:107], v[120:121], s[46:47], v[98:99] op_sel_hi:[1,0,0]
	v_ldexp_f32 v118, v104, 1
	v_ldexp_f32 v119, v105, 1
	v_pk_mul_f32 v[104:105], v[104:105], v[120:121]
	v_pk_fma_f32 v[106:107], v[120:121], v[106:107], s[48:49] op_sel_hi:[1,1,0]
	v_ldexp_f32 v125, v103, 1
	v_pk_mul_f32 v[104:105], v[104:105], v[106:107]
	v_ldexp_f32 v102, v102, 1
	v_pk_add_f32 v[106:107], v[118:119], v[104:105]
	v_mov_b32_e32 v103, v125
	v_pk_add_f32 v[118:119], v[106:107], v[118:119] neg_lo:[0,1] neg_hi:[0,1]
	v_mov_b32_e32 v110, v106
	v_pk_add_f32 v[104:105], v[104:105], v[118:119] neg_lo:[0,1] neg_hi:[0,1]
	s_nop 0
	v_pk_add_f32 v[118:119], v[102:103], v[104:105]
	v_mov_b32_e32 v115, v105
	v_mov_b32_e32 v105, v107
	v_mov_b32_e32 v103, v119
	v_pk_add_f32 v[120:121], v[106:107], v[118:119]
	v_pk_add_f32 v[102:103], v[102:103], v[104:105]
	v_pk_add_f32 v[104:105], v[122:123], v[120:121]
	v_pk_add_f32 v[114:115], v[114:115], v[124:125]
	v_mov_b32_e32 v124, v120
	v_mov_b32_e32 v125, v105
	v_pk_add_f32 v[110:111], v[124:125], v[110:111] neg_lo:[0,1] neg_hi:[0,1]
	v_mov_b32_e32 v108, v104
	v_mov_b32_e32 v124, v122
	v_mov_b32_e32 v113, v111
	v_mov_b32_e32 v126, v120
	v_pk_add_f32 v[108:109], v[108:109], v[116:117] neg_lo:[0,1] neg_hi:[0,1]
	v_pk_add_f32 v[112:113], v[124:125], v[112:113] neg_lo:[0,1] neg_hi:[0,1]
	v_pk_add_f32 v[116:117], v[126:127], v[108:109] neg_lo:[0,1] neg_hi:[0,1]
	v_mov_b32_e32 v124, v112
	v_mov_b32_e32 v125, v109
	v_mov_b32_e32 v126, v104
	v_mov_b32_e32 v127, v121
	v_mov_b32_e32 v109, v107
	v_pk_add_f32 v[124:125], v[100:101], v[124:125] neg_lo:[0,1] neg_hi:[0,1]
	v_pk_add_f32 v[108:109], v[126:127], v[108:109] neg_lo:[0,1] neg_hi:[0,1]
	v_mov_b32_e32 v101, v123
	v_pk_add_f32 v[108:109], v[114:115], v[108:109] neg_lo:[0,1] neg_hi:[0,1]
	v_pk_add_f32 v[100:101], v[100:101], v[112:113] neg_lo:[0,1] neg_hi:[0,1]
	v_pk_add_f32 v[102:103], v[102:103], v[110:111] neg_lo:[0,1] neg_hi:[0,1]
	v_pk_add_f32 v[112:113], v[116:117], v[108:109]
	v_pk_add_f32 v[110:111], v[102:103], v[100:101]
	v_mov_b32_e32 v101, v117
	v_mov_b32_e32 v103, v109
	v_pk_add_f32 v[102:103], v[100:101], v[102:103]
	v_pk_add_f32 v[106:107], v[120:121], v[106:107] neg_lo:[0,1] neg_hi:[0,1]
	v_pk_add_f32 v[102:103], v[102:103], v[124:125] neg_lo:[0,1] neg_hi:[0,1]
	v_mov_b32_e32 v108, v110
	v_mov_b32_e32 v109, v113
	v_pk_add_f32 v[106:107], v[118:119], v[106:107] neg_lo:[0,1] neg_hi:[0,1]
	v_pk_add_f32 v[108:109], v[108:109], v[102:103] neg_lo:[0,1] neg_hi:[0,1]
	v_pk_add_f32 v[102:103], v[106:107], v[102:103] neg_lo:[0,1] neg_hi:[0,1]
	v_pk_add_f32 v[100:101], v[100:101], v[108:109] neg_lo:[0,1] neg_hi:[0,1]
	v_exp_f32_e32 v119, v74
	v_pk_add_f32 v[100:101], v[102:103], v[100:101]
	v_pk_add_f32 v[102:103], v[112:113], v[110:111]
	v_add_f32_e32 v74, 1.0, v119
	v_pk_add_f32 v[106:107], v[104:105], v[102:103]
	v_add_f32_e32 v72, -1.0, v74
	v_pk_add_f32 v[104:105], v[106:107], v[104:105] neg_lo:[0,1] neg_hi:[0,1]
	v_sub_f32_e32 v73, v72, v74
	v_pk_add_f32 v[102:103], v[102:103], v[104:105] neg_lo:[0,1] neg_hi:[0,1]
	v_add_f32_e32 v73, 1.0, v73
	v_pk_add_f32 v[100:101], v[100:101], v[102:103]
	v_mul_f32_e64 v102, |v66|, s62
	v_pk_add_f32 v[100:101], v[106:107], v[100:101]
	v_exp_f32_e32 v118, v102
	v_cndmask_b32_e32 v100, v200, v100, vcc
	v_cmp_neq_f32_e32 vcc, s64, v216
	v_sub_f32_e32 v72, v119, v72
	v_add_f32_e32 v102, 1.0, v118
	v_cndmask_b32_e32 v101, v200, v101, vcc
	v_cmp_ngt_f32_e32 vcc, -1.0, v216
	v_frexp_mant_f32_e32 v104, v102
	v_add_f32_e32 v75, v72, v73
	v_cndmask_b32_e32 v101, v201, v101, vcc
	v_cmp_ngt_f32_e32 vcc, -1.0, v215
	v_frexp_mant_f32_e32 v76, v74
	v_cvt_f64_f32_e32 v[72:73], v74
	v_cndmask_b32_e32 v100, v201, v100, vcc
	v_cmp_neq_f32_e32 vcc, -1.0, v215
	v_frexp_exp_i32_f64_e32 v72, v[72:73]
	v_min_f32_e32 v66, 0, v66
	v_cndmask_b32_e32 v100, v202, v100, vcc
	v_cmp_neq_f32_e32 vcc, -1.0, v216
	s_nop 1
	v_cndmask_b32_e32 v101, v202, v101, vcc
	v_cmp_lt_f32_e64 vcc, |v216|, s65
	s_nop 1
	v_cndmask_b32_e32 v101, v101, v216, vcc
	v_cmp_lt_f32_e64 vcc, |v215|, s65
	s_nop 1
	v_cndmask_b32_e32 v100, v100, v215, vcc
	v_pk_add_f32 v[64:65], v[64:65], v[100:101] neg_lo:[0,1] neg_hi:[0,1]
	v_add_f32_e32 v100, -1.0, v102
	v_sub_f32_e32 v101, v100, v102
	v_add_f32_e32 v101, 1.0, v101
	v_sub_f32_e32 v100, v118, v100
	v_add_f32_e32 v103, v100, v101
	v_cvt_f64_f32_e32 v[100:101], v102
	v_frexp_exp_i32_f64_e32 v100, v[100:101]
	v_cmp_gt_f32_e32 vcc, s63, v104
	s_nop 1
	v_subbrev_co_u32_e32 v112, vcc, 0, v100, vcc
	v_cmp_gt_f32_e32 vcc, s63, v76
	v_sub_u32_e32 v101, 0, v112
	v_ldexp_f32 v100, v102, v101
	v_subbrev_co_u32_e32 v113, vcc, 0, v72, vcc
	v_sub_u32_e32 v72, 0, v113
	v_ldexp_f32 v102, v103, v101
	v_ldexp_f32 v101, v74, v72
	v_ldexp_f32 v103, v75, v72
	v_pk_add_f32 v[72:73], v[100:101], 1.0 op_sel_hi:[1,0]
	v_pk_add_f32 v[104:105], v[100:101], -1.0 op_sel_hi:[1,0]
	v_pk_add_f32 v[74:75], v[72:73], -1.0 op_sel_hi:[1,0]
	v_pk_add_f32 v[106:107], v[104:105], 1.0 op_sel_hi:[1,0]
	v_pk_add_f32 v[74:75], v[100:101], v[74:75] neg_lo:[0,1] neg_hi:[0,1]
	v_pk_add_f32 v[100:101], v[100:101], v[106:107] neg_lo:[0,1] neg_hi:[0,1]
	v_pk_add_f32 v[74:75], v[102:103], v[74:75]
	v_pk_add_f32 v[100:101], v[102:103], v[100:101]
	v_pk_add_f32 v[76:77], v[72:73], v[74:75]
	v_pk_add_f32 v[102:103], v[104:105], v[100:101]
	v_rcp_f32_e32 v78, v76
	v_rcp_f32_e32 v79, v77
	v_pk_add_f32 v[72:73], v[76:77], v[72:73] neg_lo:[0,1] neg_hi:[0,1]
	v_pk_add_f32 v[104:105], v[102:103], v[104:105] neg_lo:[0,1] neg_hi:[0,1]
	v_pk_add_f32 v[72:73], v[74:75], v[72:73] neg_lo:[0,1] neg_hi:[0,1]
	v_pk_mul_f32 v[74:75], v[102:103], v[78:79]
	v_pk_add_f32 v[100:101], v[100:101], v[104:105] neg_lo:[0,1] neg_hi:[0,1]
	v_pk_mul_f32 v[104:105], v[76:77], v[74:75]
	v_cmp_neq_f32_e32 vcc, s64, v118
	v_pk_fma_f32 v[106:107], v[74:75], v[76:77], v[104:105] neg_lo:[0,0,1] neg_hi:[0,0,1]
	s_nop 0
	v_pk_fma_f32 v[106:107], v[74:75], v[72:73], v[106:107]
	s_nop 0
	v_pk_add_f32 v[108:109], v[104:105], v[106:107]
	s_nop 0
	v_pk_add_f32 v[110:111], v[102:103], v[108:109] neg_lo:[0,1] neg_hi:[0,1]
	v_pk_add_f32 v[104:105], v[108:109], v[104:105] neg_lo:[0,1] neg_hi:[0,1]
	v_pk_add_f32 v[102:103], v[102:103], v[110:111] neg_lo:[0,1] neg_hi:[0,1]
	s_nop 0
	v_pk_add_f32 v[102:103], v[102:103], v[108:109] neg_lo:[0,1] neg_hi:[0,1]
	s_nop 0
	v_pk_add_f32 v[100:101], v[100:101], v[102:103]
	v_pk_add_f32 v[102:103], v[104:105], v[106:107] neg_lo:[0,1] neg_hi:[0,1]
	s_nop 0
	v_pk_add_f32 v[100:101], v[102:103], v[100:101]
	s_nop 0
	v_pk_add_f32 v[102:103], v[110:111], v[100:101]
	s_nop 0
	v_pk_mul_f32 v[104:105], v[78:79], v[102:103]
	s_nop 0
	v_pk_mul_f32 v[106:107], v[76:77], v[104:105]
	s_nop 0
	v_pk_fma_f32 v[76:77], v[104:105], v[76:77], v[106:107] neg_lo:[0,0,1] neg_hi:[0,0,1]
	s_nop 0
	v_pk_fma_f32 v[72:73], v[104:105], v[72:73], v[76:77]
	v_pk_add_f32 v[76:77], v[110:111], v[102:103] neg_lo:[0,1] neg_hi:[0,1]
	s_nop 0
	v_pk_add_f32 v[76:77], v[100:101], v[76:77]
	v_pk_add_f32 v[100:101], v[106:107], v[72:73]
	s_nop 0
	v_pk_add_f32 v[108:109], v[102:103], v[100:101] neg_lo:[0,1] neg_hi:[0,1]
	v_pk_add_f32 v[106:107], v[100:101], v[106:107] neg_lo:[0,1] neg_hi:[0,1]
	v_pk_add_f32 v[102:103], v[102:103], v[108:109] neg_lo:[0,1] neg_hi:[0,1]
	v_pk_add_f32 v[72:73], v[106:107], v[72:73] neg_lo:[0,1] neg_hi:[0,1]
	v_pk_add_f32 v[100:101], v[102:103], v[100:101] neg_lo:[0,1] neg_hi:[0,1]
	s_nop 0
	v_pk_add_f32 v[76:77], v[76:77], v[100:101]
	v_cvt_f32_i32_e32 v101, v113
	v_pk_add_f32 v[72:73], v[72:73], v[76:77]
	v_pk_add_f32 v[76:77], v[74:75], v[104:105]
	v_pk_add_f32 v[72:73], v[108:109], v[72:73]
	v_pk_add_f32 v[74:75], v[76:77], v[74:75] neg_lo:[0,1] neg_hi:[0,1]
	v_pk_mul_f32 v[72:73], v[78:79], v[72:73]
	v_pk_add_f32 v[74:75], v[104:105], v[74:75] neg_lo:[0,1] neg_hi:[0,1]
	v_cvt_f32_i32_e32 v100, v112
	v_pk_add_f32 v[72:73], v[74:75], v[72:73]
	s_nop 0
	v_pk_add_f32 v[74:75], v[76:77], v[72:73]
	s_nop 0
	v_pk_mul_f32 v[78:79], v[74:75], v[74:75]
	v_pk_add_f32 v[76:77], v[74:75], v[76:77] neg_lo:[0,1] neg_hi:[0,1]
	v_pk_fma_f32 v[98:99], v[78:79], s[46:47], v[98:99] op_sel_hi:[1,0,0]
	v_pk_add_f32 v[72:73], v[72:73], v[76:77] neg_lo:[0,1] neg_hi:[0,1]
	v_ldexp_f32 v76, v74, 1
	v_pk_fma_f32 v[98:99], v[78:79], v[98:99], s[48:49] op_sel_hi:[1,1,0]
	v_ldexp_f32 v77, v75, 1
	v_pk_mul_f32 v[74:75], v[74:75], v[78:79]
	v_pk_mul_f32 v[78:79], v[100:101], s[50:51] op_sel_hi:[1,0]
	v_pk_mul_f32 v[74:75], v[74:75], v[98:99]
	v_pk_fma_f32 v[104:105], v[100:101], s[50:51], v[78:79] op_sel_hi:[1,0,1] neg_lo:[0,0,1] neg_hi:[0,0,1]
	v_pk_add_f32 v[98:99], v[76:77], v[74:75]
	v_ldexp_f32 v103, v73, 1
	v_pk_add_f32 v[76:77], v[98:99], v[76:77] neg_lo:[0,1] neg_hi:[0,1]
	v_pk_fma_f32 v[100:101], v[100:101], s[52:53], v[104:105] op_sel_hi:[1,0,1]
	v_pk_add_f32 v[74:75], v[74:75], v[76:77] neg_lo:[0,1] neg_hi:[0,1]
	v_ldexp_f32 v72, v72, 1
	v_mov_b32_e32 v76, v78
	v_mov_b32_e32 v77, v75
	v_mov_b32_e32 v102, v100
	v_mov_b32_e32 v73, v103
	v_pk_add_f32 v[76:77], v[76:77], v[102:103]
	v_pk_add_f32 v[102:103], v[72:73], v[74:75]
	v_mov_b32_e32 v75, v99
	v_mov_b32_e32 v73, v103
	v_pk_add_f32 v[104:105], v[78:79], v[100:101]
	v_pk_add_f32 v[72:73], v[72:73], v[74:75]
	v_pk_add_f32 v[74:75], v[98:99], v[102:103]
	v_mov_b32_e32 v114, v98
	v_pk_add_f32 v[106:107], v[104:105], v[74:75]
	v_mov_b32_e32 v112, v74
	v_mov_b32_e32 v113, v107
	v_mov_b32_e32 v115, v105
	v_pk_add_f32 v[112:113], v[112:113], v[114:115] neg_lo:[0,1] neg_hi:[0,1]
	v_mov_b32_e32 v108, v106
	v_mov_b32_e32 v109, v105
	v_mov_b32_e32 v110, v104
	v_mov_b32_e32 v111, v79
	v_mov_b32_e32 v114, v104
	v_mov_b32_e32 v115, v107
	v_mov_b32_e32 v79, v113
	v_pk_add_f32 v[108:109], v[108:109], v[110:111] neg_lo:[0,1] neg_hi:[0,1]
	v_mov_b32_e32 v110, v74
	v_mov_b32_e32 v111, v101
	v_pk_add_f32 v[78:79], v[114:115], v[78:79] neg_lo:[0,1] neg_hi:[0,1]
	v_pk_add_f32 v[110:111], v[110:111], v[108:109] neg_lo:[0,1] neg_hi:[0,1]
	v_mov_b32_e32 v114, v78
	v_mov_b32_e32 v115, v109
	v_mov_b32_e32 v116, v106
	v_mov_b32_e32 v117, v75
	v_mov_b32_e32 v109, v99
	v_pk_add_f32 v[114:115], v[100:101], v[114:115] neg_lo:[0,1] neg_hi:[0,1]
	v_pk_add_f32 v[108:109], v[116:117], v[108:109] neg_lo:[0,1] neg_hi:[0,1]
	v_mov_b32_e32 v101, v105
	v_pk_add_f32 v[76:77], v[76:77], v[108:109] neg_lo:[0,1] neg_hi:[0,1]
	v_pk_add_f32 v[78:79], v[100:101], v[78:79] neg_lo:[0,1] neg_hi:[0,1]
	v_pk_add_f32 v[72:73], v[72:73], v[112:113] neg_lo:[0,1] neg_hi:[0,1]
	v_pk_add_f32 v[74:75], v[74:75], v[98:99] neg_lo:[0,1] neg_hi:[0,1]
	v_pk_add_f32 v[98:99], v[72:73], v[78:79]
	v_mov_b32_e32 v79, v111
	v_mov_b32_e32 v73, v77
	v_pk_add_f32 v[100:101], v[110:111], v[76:77]
	v_pk_add_f32 v[72:73], v[78:79], v[72:73]
	v_mov_b32_e32 v76, v98
	v_pk_add_f32 v[72:73], v[72:73], v[114:115] neg_lo:[0,1] neg_hi:[0,1]
	v_mov_b32_e32 v77, v101
	v_pk_add_f32 v[74:75], v[102:103], v[74:75] neg_lo:[0,1] neg_hi:[0,1]
	v_pk_add_f32 v[76:77], v[76:77], v[72:73] neg_lo:[0,1] neg_hi:[0,1]
	v_pk_add_f32 v[72:73], v[74:75], v[72:73] neg_lo:[0,1] neg_hi:[0,1]
	v_pk_add_f32 v[76:77], v[78:79], v[76:77] neg_lo:[0,1] neg_hi:[0,1]
	v_pk_add_f32 v[74:75], v[100:101], v[98:99]
	v_pk_add_f32 v[72:73], v[72:73], v[76:77]
	v_pk_add_f32 v[76:77], v[106:107], v[74:75]
	s_nop 0
	v_pk_add_f32 v[78:79], v[76:77], v[106:107] neg_lo:[0,1] neg_hi:[0,1]
	s_nop 0
	v_pk_add_f32 v[74:75], v[74:75], v[78:79] neg_lo:[0,1] neg_hi:[0,1]
	s_nop 0
	v_pk_add_f32 v[72:73], v[72:73], v[74:75]
	s_nop 0
	v_pk_add_f32 v[72:73], v[76:77], v[72:73]
	s_nop 0
	v_cndmask_b32_e32 v72, v200, v72, vcc
	v_cmp_neq_f32_e32 vcc, s64, v119
	s_nop 1
	v_cndmask_b32_e32 v73, v200, v73, vcc
	v_cmp_ngt_f32_e32 vcc, -1.0, v119
	s_nop 1
	v_cndmask_b32_e32 v73, v201, v73, vcc
	v_cmp_ngt_f32_e32 vcc, -1.0, v118
	s_nop 1
	v_cndmask_b32_e32 v72, v201, v72, vcc
	v_cmp_neq_f32_e32 vcc, -1.0, v118
	s_nop 1
	v_cndmask_b32_e32 v72, v202, v72, vcc
	v_cmp_neq_f32_e32 vcc, -1.0, v119
	s_nop 1
	v_cndmask_b32_e32 v73, v202, v73, vcc
	v_cmp_lt_f32_e64 vcc, |v119|, s65
	s_nop 1
	v_cndmask_b32_e32 v73, v73, v119, vcc
	v_cmp_lt_f32_e64 vcc, |v118|, s65
	s_nop 1
	v_cndmask_b32_e32 v72, v72, v118, vcc
	v_pk_add_f32 v[66:67], v[66:67], v[72:73] neg_lo:[0,1] neg_hi:[0,1]
	global_store_dwordx4 v199, v[68:71], s[56:57] offset:32
	global_store_dwordx4 v199, v[64:67], s[56:57] offset:48

.LBB0_282:
	s_or_b64 exec, exec, s[56:57]
	global_load_dwordx4 v[94:97], v[140:141], off
	ds_read_b128 v[98:101], v230 offset:3072
	ds_read_b128 v[102:105], v230 offset:2048
	ds_read_b128 v[106:109], v230 offset:1024
	ds_read_b128 v[110:113], v230
	v_mul_f32_e32 v76, v76, v92
	v_mul_f32_e32 v74, v74, v92
	v_mul_f32_e32 v72, v72, v92
	v_mul_f32_e32 v70, v70, v92
	v_mul_f32_e32 v66, v66, v92
	v_mul_f32_e32 v64, v64, v92
	v_mul_f32_e32 v68, v68, v92
	v_mul_f32_e32 v90, v90, v92
	s_waitcnt vmcnt(0)
	v_mul_f32_e32 v76, v76, v94
	v_mul_f32_e32 v74, v74, v96
	s_waitcnt vmcnt(0)
	s_waitcnt lgkmcnt(1)
	v_pk_fma_f32 v[108:109], v[108:109], v[76:77], 0 op_sel_hi:[1,0,0]
	s_waitcnt vmcnt(0)
	s_waitcnt lgkmcnt(0)
	v_pk_fma_f32 v[78:79], v[112:113], v[76:77], 0 op_sel_hi:[1,0,0]
	v_pk_fma_f32 v[88:89], v[110:111], v[76:77], 0 op_sel_hi:[1,0,0]
	v_pk_fma_f32 v[106:107], v[106:107], v[76:77], 0 op_sel_hi:[1,0,0]
	v_mul_f32_e32 v76, v77, v92
	v_mul_f32_e32 v76, v76, v95
	v_pk_fma_f32 v[94:95], v[104:105], v[76:77], v[78:79] op_sel_hi:[1,0,1]
	v_pk_fma_f32 v[88:89], v[102:103], v[76:77], v[88:89] op_sel_hi:[1,0,1]
	v_pk_fma_f32 v[110:111], v[76:77], v[100:101], v[108:109] op_sel_hi:[0,1,1]
	v_pk_fma_f32 v[112:113], v[76:77], v[98:99], v[106:107] op_sel_hi:[0,1,1]
	ds_read_b128 v[76:79], v230 offset:19456
	ds_read_b128 v[98:101], v230 offset:18432
	ds_read_b128 v[102:105], v230 offset:17408
	ds_read_b128 v[106:109], v230 offset:16384
	s_waitcnt vmcnt(0)
	s_waitcnt lgkmcnt(1)
	v_pk_fma_f32 v[102:103], v[74:75], v[102:103], v[112:113] op_sel_hi:[0,1,1]
	s_waitcnt vmcnt(0)
	s_waitcnt lgkmcnt(0)
	v_pk_fma_f32 v[88:89], v[74:75], v[106:107], v[88:89] op_sel_hi:[0,1,1]
	v_pk_fma_f32 v[94:95], v[74:75], v[108:109], v[94:95] op_sel_hi:[0,1,1]
	v_pk_fma_f32 v[104:105], v[74:75], v[104:105], v[110:111] op_sel_hi:[0,1,1]
	v_mul_f32_e32 v74, v75, v92
	v_mul_f32_e32 v74, v74, v97
	v_pk_fma_f32 v[110:111], v[74:75], v[100:101], v[94:95] op_sel_hi:[0,1,1]
	v_pk_fma_f32 v[88:89], v[74:75], v[98:99], v[88:89] op_sel_hi:[0,1,1]
	v_pk_fma_f32 v[78:79], v[74:75], v[78:79], v[104:105] op_sel_hi:[0,1,1]
	v_pk_fma_f32 v[112:113], v[74:75], v[76:77], v[102:103] op_sel_hi:[0,1,1]
	global_load_dwordx4 v[74:77], v[140:141], off offset:1024
	ds_read_b128 v[94:97], v230 offset:35840
	ds_read_b128 v[98:101], v230 offset:34816
	ds_read_b128 v[102:105], v230 offset:33792
	ds_read_b128 v[106:109], v230 offset:32768
	s_waitcnt vmcnt(0)
	v_mul_f32_e32 v72, v72, v74
	v_mul_f32_e32 v70, v70, v76
	s_waitcnt vmcnt(0)
	s_waitcnt lgkmcnt(1)
	v_pk_fma_f32 v[102:103], v[102:103], v[72:73], v[112:113] op_sel_hi:[1,0,1]
	s_waitcnt vmcnt(0)
	s_waitcnt lgkmcnt(0)
	v_pk_fma_f32 v[88:89], v[106:107], v[72:73], v[88:89] op_sel_hi:[1,0,1]
	v_pk_fma_f32 v[106:107], v[108:109], v[72:73], v[110:111] op_sel_hi:[1,0,1]
	v_pk_fma_f32 v[78:79], v[104:105], v[72:73], v[78:79] op_sel_hi:[1,0,1]
	v_mul_f32_e32 v72, v73, v92
	v_mul_f32_e32 v72, v72, v75
	v_pk_fma_f32 v[106:107], v[100:101], v[72:73], v[106:107] op_sel_hi:[1,0,1]
	v_pk_fma_f32 v[88:89], v[98:99], v[72:73], v[88:89] op_sel_hi:[1,0,1]
	v_pk_fma_f32 v[78:79], v[72:73], v[96:97], v[78:79] op_sel_hi:[0,1,1]
	v_pk_fma_f32 v[108:109], v[72:73], v[94:95], v[102:103] op_sel_hi:[0,1,1]
	ds_read_b128 v[72:75], v230 offset:52224
	ds_read_b128 v[94:97], v230 offset:51200
	ds_read_b128 v[98:101], v230 offset:50176
	ds_read_b128 v[102:105], v230 offset:49152
	s_waitcnt vmcnt(0)
	s_waitcnt lgkmcnt(1)
	v_pk_fma_f32 v[98:99], v[70:71], v[98:99], v[108:109] op_sel_hi:[0,1,1]
	s_waitcnt vmcnt(0)
	s_waitcnt lgkmcnt(0)
	v_pk_fma_f32 v[88:89], v[70:71], v[102:103], v[88:89] op_sel_hi:[0,1,1]
	v_pk_fma_f32 v[102:103], v[70:71], v[104:105], v[106:107] op_sel_hi:[0,1,1]
	v_pk_fma_f32 v[78:79], v[70:71], v[100:101], v[78:79] op_sel_hi:[0,1,1]
	v_mul_f32_e32 v70, v71, v92
	v_mul_f32_e32 v70, v70, v77
	v_pk_fma_f32 v[106:107], v[70:71], v[96:97], v[102:103] op_sel_hi:[0,1,1]
	v_pk_fma_f32 v[88:89], v[70:71], v[94:95], v[88:89] op_sel_hi:[0,1,1]
	v_pk_fma_f32 v[78:79], v[70:71], v[74:75], v[78:79] op_sel_hi:[0,1,1]
	v_pk_fma_f32 v[108:109], v[70:71], v[72:73], v[98:99] op_sel_hi:[0,1,1]
	global_load_dwordx4 v[70:73], v[140:141], off offset:2048
	ds_read_b128 v[74:77], v231 offset:3072
	ds_read_b128 v[94:97], v231 offset:2048
	ds_read_b128 v[98:101], v231 offset:1024
	ds_read_b128 v[102:105], v231
	s_waitcnt vmcnt(0)
	v_mul_f32_e32 v66, v66, v70
	v_mul_f32_e32 v64, v64, v72
	s_waitcnt vmcnt(0)
	s_waitcnt lgkmcnt(1)
	v_pk_fma_f32 v[98:99], v[98:99], v[66:67], v[108:109] op_sel_hi:[1,0,1]
	s_waitcnt vmcnt(0)
	s_waitcnt lgkmcnt(0)
	v_pk_fma_f32 v[88:89], v[102:103], v[66:67], v[88:89] op_sel_hi:[1,0,1]
	v_pk_fma_f32 v[102:103], v[104:105], v[66:67], v[106:107] op_sel_hi:[1,0,1]
	v_pk_fma_f32 v[78:79], v[100:101], v[66:67], v[78:79] op_sel_hi:[1,0,1]
	v_mul_f32_e32 v66, v67, v92
	v_mul_f32_e32 v66, v66, v71
	v_pk_fma_f32 v[70:71], v[96:97], v[66:67], v[102:103] op_sel_hi:[1,0,1]
	v_pk_fma_f32 v[88:89], v[94:95], v[66:67], v[88:89] op_sel_hi:[1,0,1]
	v_pk_fma_f32 v[78:79], v[66:67], v[76:77], v[78:79] op_sel_hi:[0,1,1]
	v_pk_fma_f32 v[66:67], v[66:67], v[74:75], v[98:99] op_sel_hi:[0,1,1]
	ds_read_b128 v[74:77], v231 offset:19456
	ds_read_b128 v[94:97], v231 offset:18432
	ds_read_b128 v[98:101], v231 offset:17408
	ds_read_b128 v[102:105], v231 offset:16384
	s_waitcnt vmcnt(0)
	s_waitcnt lgkmcnt(1)
	v_pk_fma_f32 v[66:67], v[64:65], v[98:99], v[66:67] op_sel_hi:[0,1,1]
	s_waitcnt vmcnt(0)
	s_waitcnt lgkmcnt(0)
	v_pk_fma_f32 v[88:89], v[64:65], v[102:103], v[88:89] op_sel_hi:[0,1,1]
	v_pk_fma_f32 v[70:71], v[64:65], v[104:105], v[70:71] op_sel_hi:[0,1,1]
	v_pk_fma_f32 v[78:79], v[64:65], v[100:101], v[78:79] op_sel_hi:[0,1,1]
	v_mul_f32_e32 v64, v65, v92
	v_mul_f32_e32 v64, v64, v73
	v_pk_fma_f32 v[102:103], v[64:65], v[96:97], v[70:71] op_sel_hi:[0,1,1]
	v_pk_fma_f32 v[88:89], v[64:65], v[94:95], v[88:89] op_sel_hi:[0,1,1]
	v_pk_fma_f32 v[78:79], v[64:65], v[76:77], v[78:79] op_sel_hi:[0,1,1]
	v_pk_fma_f32 v[104:105], v[64:65], v[74:75], v[66:67] op_sel_hi:[0,1,1]
	global_load_dwordx4 v[64:67], v[140:141], off offset:3072
	ds_read_b128 v[70:73], v231 offset:35840
	ds_read_b128 v[74:77], v231 offset:34816
	ds_read_b128 v[94:97], v231 offset:33792
	ds_read_b128 v[98:101], v231 offset:32768
	s_waitcnt vmcnt(0)
	v_mul_f32_e32 v64, v68, v64
	v_mul_f32_e32 v66, v90, v66
	s_waitcnt vmcnt(0)
	s_waitcnt lgkmcnt(1)
	v_pk_fma_f32 v[78:79], v[96:97], v[64:65], v[78:79] op_sel_hi:[1,0,1]
	s_waitcnt vmcnt(0)
	s_waitcnt lgkmcnt(0)
	v_pk_fma_f32 v[88:89], v[98:99], v[64:65], v[88:89] op_sel_hi:[1,0,1]
	v_pk_fma_f32 v[98:99], v[100:101], v[64:65], v[102:103] op_sel_hi:[1,0,1]
	v_pk_fma_f32 v[100:101], v[94:95], v[64:65], v[104:105] op_sel_hi:[1,0,1]
	v_mul_f32_e32 v64, v69, v92
	v_mul_f32_e32 v68, v64, v65
	v_pk_fma_f32 v[94:95], v[76:77], v[68:69], v[98:99] op_sel_hi:[1,0,1]
	v_pk_fma_f32 v[96:97], v[74:75], v[68:69], v[88:89] op_sel_hi:[1,0,1]
	v_pk_fma_f32 v[64:65], v[68:69], v[72:73], v[78:79] op_sel_hi:[0,1,1]
	v_pk_fma_f32 v[88:89], v[68:69], v[70:71], v[100:101] op_sel_hi:[0,1,1]
	ds_read_b128 v[68:71], v231 offset:52224
	ds_read_b128 v[72:75], v231 offset:51200
	ds_read_b128 v[76:79], v231 offset:50176
	ds_read_b128 v[98:101], v231 offset:49152
	s_waitcnt vmcnt(0)
	s_waitcnt lgkmcnt(1)
	v_pk_fma_f32 v[76:77], v[66:67], v[76:77], v[88:89] op_sel_hi:[0,1,1]
	s_waitcnt vmcnt(0)
	s_waitcnt lgkmcnt(0)
	v_pk_fma_f32 v[96:97], v[66:67], v[98:99], v[96:97] op_sel_hi:[0,1,1]
	v_pk_fma_f32 v[94:95], v[66:67], v[100:101], v[94:95] op_sel_hi:[0,1,1]
	v_pk_fma_f32 v[64:65], v[66:67], v[78:79], v[64:65] op_sel_hi:[0,1,1]
	v_mul_f32_e32 v66, v91, v92
	v_mul_f32_e32 v78, v66, v67
	v_pk_fma_f32 v[64:65], v[78:79], v[70:71], v[64:65] op_sel_hi:[0,1,1]
	v_pk_fma_f32 v[70:71], v[78:79], v[68:69], v[76:77] op_sel_hi:[0,1,1]
	ds_bpermute_b32 v77, v190, v64
	ds_bpermute_b32 v68, v190, v70
	v_pk_fma_f32 v[66:67], v[78:79], v[74:75], v[94:95] op_sel_hi:[0,1,1]
	v_pk_fma_f32 v[72:73], v[78:79], v[72:73], v[96:97] op_sel_hi:[0,1,1]
	ds_bpermute_b32 v74, v190, v72
	s_waitcnt lgkmcnt(2)
	v_add_f32_e32 v64, v64, v77
	ds_bpermute_b32 v77, v191, v64
	s_waitcnt lgkmcnt(2)
	v_add_f32_e32 v68, v70, v68
	ds_bpermute_b32 v75, v190, v73
	ds_bpermute_b32 v70, v190, v71
	ds_bpermute_b32 v76, v190, v66
	s_waitcnt lgkmcnt(3)
	v_add_f32_e32 v64, v64, v77
	ds_bpermute_b32 v77, v192, v64
	s_waitcnt lgkmcnt(3)
	v_pk_add_f32 v[72:73], v[72:73], v[74:75]
	s_waitcnt lgkmcnt(2)
	v_add_f32_e32 v70, v71, v70
	ds_bpermute_b32 v69, v191, v68
	ds_bpermute_b32 v74, v191, v72
	s_waitcnt lgkmcnt(2)
	v_add_f32_e32 v64, v64, v77
	ds_bpermute_b32 v77, v193, v64
	ds_bpermute_b32 v75, v191, v73
	ds_bpermute_b32 v71, v191, v70
	s_waitcnt lgkmcnt(4)
	v_add_f32_e32 v68, v68, v69
	ds_bpermute_b32 v69, v192, v68
	s_waitcnt lgkmcnt(3)
	v_add_f32_e32 v64, v64, v77
	ds_bpermute_b32 v77, v194, v64
	s_waitcnt lgkmcnt(3)
	v_pk_add_f32 v[72:73], v[72:73], v[74:75]
	s_waitcnt lgkmcnt(2)
	v_add_f32_e32 v70, v70, v71
	ds_bpermute_b32 v74, v192, v72
	ds_bpermute_b32 v75, v192, v73
	s_waitcnt lgkmcnt(2)
	v_add_f32_e32 v88, v64, v77
	ds_bpermute_b32 v77, v190, v67
	ds_bpermute_b32 v64, v190, v65
	ds_bpermute_b32 v71, v192, v70
	v_add_f32_e32 v68, v68, v69
	s_waitcnt lgkmcnt(3)
	v_pk_add_f32 v[72:73], v[72:73], v[74:75]
	s_waitcnt lgkmcnt(2)
	v_pk_add_f32 v[66:67], v[66:67], v[76:77]
	s_waitcnt lgkmcnt(1)
	v_add_f32_e32 v64, v65, v64
	ds_bpermute_b32 v76, v191, v66
	ds_bpermute_b32 v77, v191, v67
	ds_bpermute_b32 v65, v191, v64
	s_waitcnt lgkmcnt(3)
	v_add_f32_e32 v70, v70, v71
	ds_bpermute_b32 v69, v193, v68
	ds_bpermute_b32 v74, v193, v72
	s_waitcnt lgkmcnt(3)
	v_pk_add_f32 v[66:67], v[66:67], v[76:77]
	s_waitcnt lgkmcnt(2)
	v_add_f32_e32 v64, v64, v65
	ds_bpermute_b32 v76, v192, v66
	ds_bpermute_b32 v77, v192, v67
	ds_bpermute_b32 v65, v192, v64
	ds_bpermute_b32 v75, v193, v73
	ds_bpermute_b32 v71, v193, v70
	s_waitcnt lgkmcnt(6)
	v_add_f32_e32 v68, v68, v69
	s_waitcnt lgkmcnt(3)
	v_pk_add_f32 v[66:67], v[66:67], v[76:77]
	s_waitcnt lgkmcnt(2)
	v_add_f32_e32 v64, v64, v65
	ds_bpermute_b32 v76, v193, v66
	ds_bpermute_b32 v77, v193, v67
	ds_bpermute_b32 v65, v193, v64
	s_waitcnt lgkmcnt(4)
	v_pk_add_f32 v[72:73], v[72:73], v[74:75]
	s_waitcnt lgkmcnt(3)
	v_add_f32_e32 v70, v70, v71
	ds_bpermute_b32 v69, v194, v68
	s_waitcnt lgkmcnt(2)
	v_pk_add_f32 v[66:67], v[66:67], v[76:77]
	s_waitcnt lgkmcnt(1)
	v_add_f32_e32 v64, v64, v65
	ds_bpermute_b32 v74, v194, v72
	ds_bpermute_b32 v75, v194, v73
	ds_bpermute_b32 v71, v194, v70
	ds_bpermute_b32 v76, v194, v66
	ds_bpermute_b32 v77, v194, v67
	ds_bpermute_b32 v65, v194, v64
	s_waitcnt lgkmcnt(6)
	v_add_f32_e32 v68, v68, v69
	s_waitcnt lgkmcnt(4)
	v_pk_add_f32 v[72:73], v[72:73], v[74:75]
	s_waitcnt lgkmcnt(3)
	v_add_f32_e32 v70, v70, v71
	s_waitcnt lgkmcnt(1)
	v_pk_add_f32 v[76:77], v[66:67], v[76:77]
	s_waitcnt lgkmcnt(0)
	v_add_f32_e32 v90, v64, v65
	ds_bpermute_b32 v69, v195, v68
	ds_bpermute_b32 v74, v195, v72
	ds_bpermute_b32 v75, v195, v73
	ds_bpermute_b32 v71, v195, v70
	ds_bpermute_b32 v89, v195, v88
	ds_bpermute_b32 v78, v195, v76
	ds_bpermute_b32 v79, v195, v77
	ds_bpermute_b32 v91, v195, v90
	s_and_saveexec_b64 s[12:13], s[4:5]
	s_cbranch_execz .LBB0_284
	global_load_dwordx4 v[64:67], v129, s[20:21] offset:16
	s_waitcnt lgkmcnt(0)
	v_add_f32_e32 v203, v90, v91
	v_add_f32_e32 v90, v68, v69
	v_add_f32_e32 v91, v70, v71
	global_load_dwordx4 v[68:71], v129, s[20:21]
	v_add_f32_e32 v204, v88, v89
	v_mov_b64_e32 v[88:89], s[44:45]
	v_pk_add_f32 v[72:73], v[72:73], v[74:75]
	v_pk_add_f32 v[76:77], v[76:77], v[78:79]
	s_add_u32 s56, s16, s40
	s_addc_u32 s57, s17, s41
	s_waitcnt vmcnt(1)
	v_add_f32_e32 v64, v90, v64
	v_mul_f32_e64 v90, |v64|, s62
	v_add_f32_e32 v65, v91, v65
	v_exp_f32_e32 v205, v90
	v_mul_f32_e64 v91, |v65|, s62
	v_exp_f32_e32 v206, v91
	v_add_f32_e32 v66, v204, v66
	v_add_f32_e32 v94, 1.0, v205
	v_frexp_mant_f32_e32 v97, v94
	v_cvt_f64_f32_e32 v[90:91], v94
	v_add_f32_e32 v95, 1.0, v206
	v_frexp_exp_i32_f64_e32 v90, v[90:91]
	v_cmp_gt_f32_e32 vcc, s63, v97
	v_add_f32_e32 v96, -1.0, v94
	v_add_f32_e32 v98, -1.0, v95
	v_frexp_mant_f32_e32 v99, v95
	v_cvt_f64_f32_e32 v[92:93], v95
	v_subbrev_co_u32_e32 v90, vcc, 0, v90, vcc
	v_sub_f32_e32 v100, v96, v94
	v_sub_f32_e32 v91, v98, v95
	v_frexp_exp_i32_f64_e32 v92, v[92:93]
	v_cmp_gt_f32_e32 vcc, s63, v99
	v_sub_f32_e32 v96, v205, v96
	v_sub_f32_e32 v98, v206, v98
	v_add_f32_e32 v93, 1.0, v100
	v_add_f32_e32 v91, 1.0, v91
	v_subbrev_co_u32_e32 v92, vcc, 0, v92, vcc
	v_add_f32_e32 v93, v96, v93
	v_sub_u32_e32 v96, 0, v90
	v_add_f32_e32 v97, v98, v91
	v_sub_u32_e32 v98, 0, v92
	v_cvt_f32_i32_e32 v91, v92
	v_cvt_f32_i32_e32 v90, v90
	v_ldexp_f32 v92, v94, v96
	v_ldexp_f32 v94, v93, v96
	v_ldexp_f32 v93, v95, v98
	v_ldexp_f32 v95, v97, v98
	v_pk_add_f32 v[96:97], v[92:93], 1.0 op_sel_hi:[1,0]
	v_pk_add_f32 v[98:99], v[92:93], -1.0 op_sel_hi:[1,0]
	v_pk_add_f32 v[100:101], v[96:97], -1.0 op_sel_hi:[1,0]
	v_pk_add_f32 v[102:103], v[98:99], 1.0 op_sel_hi:[1,0]
	v_pk_add_f32 v[100:101], v[92:93], v[100:101] neg_lo:[0,1] neg_hi:[0,1]
	v_pk_add_f32 v[92:93], v[92:93], v[102:103] neg_lo:[0,1] neg_hi:[0,1]
	v_pk_mul_f32 v[102:103], v[90:91], s[50:51] op_sel_hi:[1,0]
	v_pk_add_f32 v[100:101], v[94:95], v[100:101]
	v_pk_add_f32 v[92:93], v[94:95], v[92:93]
	v_pk_fma_f32 v[94:95], v[90:91], s[50:51], v[102:103] op_sel_hi:[1,0,1] neg_lo:[0,0,1] neg_hi:[0,0,1]
	v_pk_add_f32 v[108:109], v[96:97], v[100:101]
	v_pk_fma_f32 v[90:91], v[90:91], s[52:53], v[94:95] op_sel_hi:[1,0,1]
	v_rcp_f32_e32 v94, v108
	v_rcp_f32_e32 v95, v109
	v_pk_add_f32 v[110:111], v[98:99], v[92:93]
	v_pk_add_f32 v[96:97], v[108:109], v[96:97] neg_lo:[0,1] neg_hi:[0,1]
	v_pk_add_f32 v[98:99], v[110:111], v[98:99] neg_lo:[0,1] neg_hi:[0,1]
	v_pk_mul_f32 v[118:119], v[110:111], v[94:95]
	v_pk_add_f32 v[96:97], v[100:101], v[96:97] neg_lo:[0,1] neg_hi:[0,1]
	v_pk_mul_f32 v[120:121], v[108:109], v[118:119]
	v_pk_add_f32 v[92:93], v[92:93], v[98:99] neg_lo:[0,1] neg_hi:[0,1]
	v_pk_fma_f32 v[122:123], v[118:119], v[108:109], v[120:121] neg_lo:[0,0,1] neg_hi:[0,0,1]
	v_pk_add_f32 v[112:113], v[102:103], v[90:91]
	v_pk_fma_f32 v[122:123], v[118:119], v[96:97], v[122:123]
	v_mov_b32_e32 v104, v102
	v_pk_add_f32 v[124:125], v[120:121], v[122:123]
	v_mov_b32_e32 v114, v90
	v_pk_add_f32 v[126:127], v[110:111], v[124:125] neg_lo:[0,1] neg_hi:[0,1]
	v_pk_add_f32 v[120:121], v[124:125], v[120:121] neg_lo:[0,1] neg_hi:[0,1]
	v_pk_add_f32 v[110:111], v[110:111], v[126:127] neg_lo:[0,1] neg_hi:[0,1]
	v_pk_add_f32 v[120:121], v[120:121], v[122:123] neg_lo:[0,1] neg_hi:[0,1]
	v_pk_add_f32 v[110:111], v[110:111], v[124:125] neg_lo:[0,1] neg_hi:[0,1]
	v_mov_b32_e32 v101, v113
	v_pk_add_f32 v[92:93], v[92:93], v[110:111]
	v_mov_b32_e32 v107, v103
	v_pk_add_f32 v[92:93], v[120:121], v[92:93]
	v_mov_b32_e32 v99, v113
	v_pk_add_f32 v[110:111], v[126:127], v[92:93]
	v_mov_b32_e32 v106, v112
	v_pk_mul_f32 v[120:121], v[94:95], v[110:111]
	v_pk_add_f32 v[122:123], v[126:127], v[110:111] neg_lo:[0,1] neg_hi:[0,1]
	v_pk_mul_f32 v[124:125], v[108:109], v[120:121]
	v_pk_add_f32 v[92:93], v[92:93], v[122:123]
	v_pk_add_f32 v[122:123], v[118:119], v[120:121]
	v_pk_fma_f32 v[108:109], v[120:121], v[108:109], v[124:125] neg_lo:[0,0,1] neg_hi:[0,0,1]
	v_pk_add_f32 v[118:119], v[122:123], v[118:119] neg_lo:[0,1] neg_hi:[0,1]
	v_pk_fma_f32 v[96:97], v[120:121], v[96:97], v[108:109]
	v_pk_add_f32 v[108:109], v[120:121], v[118:119] neg_lo:[0,1] neg_hi:[0,1]
	v_pk_add_f32 v[118:119], v[124:125], v[96:97]
	v_mov_b32_e32 v117, v91
	v_pk_add_f32 v[120:121], v[118:119], v[124:125] neg_lo:[0,1] neg_hi:[0,1]
	v_pk_add_f32 v[124:125], v[110:111], v[118:119] neg_lo:[0,1] neg_hi:[0,1]
	v_pk_add_f32 v[96:97], v[120:121], v[96:97] neg_lo:[0,1] neg_hi:[0,1]
	v_pk_add_f32 v[110:111], v[110:111], v[124:125] neg_lo:[0,1] neg_hi:[0,1]
	v_cmp_neq_f32_e32 vcc, s64, v205
	v_pk_add_f32 v[110:111], v[110:111], v[118:119] neg_lo:[0,1] neg_hi:[0,1]
	v_add_f32_e32 v67, v203, v67
	v_pk_add_f32 v[92:93], v[92:93], v[110:111]
	v_mul_f32_e64 v74, |v67|, s62
	v_pk_add_f32 v[92:93], v[96:97], v[92:93]
	v_min_f32_e32 v64, 0, v64
	v_pk_add_f32 v[92:93], v[124:125], v[92:93]
	v_min_f32_e32 v65, 0, v65
	v_pk_mul_f32 v[92:93], v[94:95], v[92:93]
	s_waitcnt vmcnt(0)
	v_pk_add_f32 v[68:69], v[72:73], v[68:69]
	v_pk_add_f32 v[92:93], v[108:109], v[92:93]
	v_pk_add_f32 v[70:71], v[76:77], v[70:71]
	v_pk_add_f32 v[94:95], v[122:123], v[92:93]
	v_min_f32_e32 v67, 0, v67
	v_pk_add_f32 v[96:97], v[94:95], v[122:123] neg_lo:[0,1] neg_hi:[0,1]
	v_pk_mul_f32 v[110:111], v[94:95], v[94:95]
	v_pk_add_f32 v[92:93], v[92:93], v[96:97] neg_lo:[0,1] neg_hi:[0,1]
	v_pk_fma_f32 v[96:97], v[110:111], s[46:47], v[88:89] op_sel_hi:[1,0,0]
	v_ldexp_f32 v108, v94, 1
	v_ldexp_f32 v109, v95, 1
	v_pk_mul_f32 v[94:95], v[94:95], v[110:111]
	v_pk_fma_f32 v[96:97], v[110:111], v[96:97], s[48:49] op_sel_hi:[1,1,0]
	v_ldexp_f32 v115, v93, 1
	v_pk_mul_f32 v[94:95], v[94:95], v[96:97]
	v_ldexp_f32 v92, v92, 1
	v_pk_add_f32 v[96:97], v[108:109], v[94:95]
	v_mov_b32_e32 v93, v115
	v_pk_add_f32 v[108:109], v[96:97], v[108:109] neg_lo:[0,1] neg_hi:[0,1]
	v_mov_b32_e32 v100, v96
	v_pk_add_f32 v[94:95], v[94:95], v[108:109] neg_lo:[0,1] neg_hi:[0,1]
	s_nop 0
	v_pk_add_f32 v[108:109], v[92:93], v[94:95]
	v_mov_b32_e32 v105, v95
	v_mov_b32_e32 v95, v97
	v_mov_b32_e32 v93, v109
	v_pk_add_f32 v[110:111], v[96:97], v[108:109]
	v_pk_add_f32 v[92:93], v[92:93], v[94:95]
	v_pk_add_f32 v[94:95], v[112:113], v[110:111]
	v_pk_add_f32 v[104:105], v[104:105], v[114:115]
	v_mov_b32_e32 v114, v110
	v_mov_b32_e32 v115, v95
	v_pk_add_f32 v[100:101], v[114:115], v[100:101] neg_lo:[0,1] neg_hi:[0,1]
	v_mov_b32_e32 v98, v94
	v_mov_b32_e32 v114, v112
	v_mov_b32_e32 v103, v101
	v_mov_b32_e32 v116, v110
	v_pk_add_f32 v[98:99], v[98:99], v[106:107] neg_lo:[0,1] neg_hi:[0,1]
	v_pk_add_f32 v[102:103], v[114:115], v[102:103] neg_lo:[0,1] neg_hi:[0,1]
	v_pk_add_f32 v[106:107], v[116:117], v[98:99] neg_lo:[0,1] neg_hi:[0,1]
	v_mov_b32_e32 v114, v102
	v_mov_b32_e32 v115, v99
	v_mov_b32_e32 v116, v94
	v_mov_b32_e32 v117, v111
	v_mov_b32_e32 v99, v97
	v_pk_add_f32 v[114:115], v[90:91], v[114:115] neg_lo:[0,1] neg_hi:[0,1]
	v_pk_add_f32 v[98:99], v[116:117], v[98:99] neg_lo:[0,1] neg_hi:[0,1]
	v_mov_b32_e32 v91, v113
	v_pk_add_f32 v[98:99], v[104:105], v[98:99] neg_lo:[0,1] neg_hi:[0,1]
	v_pk_add_f32 v[90:91], v[90:91], v[102:103] neg_lo:[0,1] neg_hi:[0,1]
	v_pk_add_f32 v[92:93], v[92:93], v[100:101] neg_lo:[0,1] neg_hi:[0,1]
	v_pk_add_f32 v[102:103], v[106:107], v[98:99]
	v_pk_add_f32 v[100:101], v[92:93], v[90:91]
	v_mov_b32_e32 v91, v107
	v_mov_b32_e32 v93, v99
	v_pk_add_f32 v[92:93], v[90:91], v[92:93]
	v_pk_add_f32 v[96:97], v[110:111], v[96:97] neg_lo:[0,1] neg_hi:[0,1]
	v_pk_add_f32 v[92:93], v[92:93], v[114:115] neg_lo:[0,1] neg_hi:[0,1]
	v_mov_b32_e32 v98, v100
	v_mov_b32_e32 v99, v103
	v_pk_add_f32 v[96:97], v[108:109], v[96:97] neg_lo:[0,1] neg_hi:[0,1]
	v_pk_add_f32 v[98:99], v[98:99], v[92:93] neg_lo:[0,1] neg_hi:[0,1]
	v_pk_add_f32 v[92:93], v[96:97], v[92:93] neg_lo:[0,1] neg_hi:[0,1]
	v_pk_add_f32 v[90:91], v[90:91], v[98:99] neg_lo:[0,1] neg_hi:[0,1]
	v_exp_f32_e32 v109, v74
	v_pk_add_f32 v[90:91], v[92:93], v[90:91]
	v_pk_add_f32 v[92:93], v[102:103], v[100:101]
	v_add_f32_e32 v74, 1.0, v109
	v_pk_add_f32 v[96:97], v[94:95], v[92:93]
	v_add_f32_e32 v72, -1.0, v74
	v_pk_add_f32 v[94:95], v[96:97], v[94:95] neg_lo:[0,1] neg_hi:[0,1]
	v_sub_f32_e32 v73, v72, v74
	v_pk_add_f32 v[92:93], v[92:93], v[94:95] neg_lo:[0,1] neg_hi:[0,1]
	v_add_f32_e32 v73, 1.0, v73
	v_pk_add_f32 v[90:91], v[90:91], v[92:93]
	v_mul_f32_e64 v92, |v66|, s62
	v_pk_add_f32 v[90:91], v[96:97], v[90:91]
	v_exp_f32_e32 v108, v92
	v_cndmask_b32_e32 v90, v200, v90, vcc
	v_cmp_neq_f32_e32 vcc, s64, v206
	v_sub_f32_e32 v72, v109, v72
	v_add_f32_e32 v92, 1.0, v108
	v_cndmask_b32_e32 v91, v200, v91, vcc
	v_cmp_ngt_f32_e32 vcc, -1.0, v206
	v_frexp_mant_f32_e32 v94, v92
	v_add_f32_e32 v75, v72, v73
	v_cndmask_b32_e32 v91, v201, v91, vcc
	v_cmp_ngt_f32_e32 vcc, -1.0, v205
	v_frexp_mant_f32_e32 v76, v74
	v_cvt_f64_f32_e32 v[72:73], v74
	v_cndmask_b32_e32 v90, v201, v90, vcc
	v_cmp_neq_f32_e32 vcc, -1.0, v205
	v_frexp_exp_i32_f64_e32 v72, v[72:73]
	v_min_f32_e32 v66, 0, v66
	v_cndmask_b32_e32 v90, v202, v90, vcc
	v_cmp_neq_f32_e32 vcc, -1.0, v206
	s_nop 1
	v_cndmask_b32_e32 v91, v202, v91, vcc
	v_cmp_lt_f32_e64 vcc, |v206|, s65
	s_nop 1
	v_cndmask_b32_e32 v91, v91, v206, vcc
	v_cmp_lt_f32_e64 vcc, |v205|, s65
	s_nop 1
	v_cndmask_b32_e32 v90, v90, v205, vcc
	v_pk_add_f32 v[64:65], v[64:65], v[90:91] neg_lo:[0,1] neg_hi:[0,1]
	v_add_f32_e32 v90, -1.0, v92
	v_sub_f32_e32 v91, v90, v92
	v_add_f32_e32 v91, 1.0, v91
	v_sub_f32_e32 v90, v108, v90
	v_add_f32_e32 v93, v90, v91
	v_cvt_f64_f32_e32 v[90:91], v92
	v_frexp_exp_i32_f64_e32 v90, v[90:91]
	v_cmp_gt_f32_e32 vcc, s63, v94
	s_nop 1
	v_subbrev_co_u32_e32 v102, vcc, 0, v90, vcc
	v_cmp_gt_f32_e32 vcc, s63, v76
	v_sub_u32_e32 v91, 0, v102
	v_ldexp_f32 v90, v92, v91
	v_subbrev_co_u32_e32 v103, vcc, 0, v72, vcc
	v_sub_u32_e32 v72, 0, v103
	v_ldexp_f32 v92, v93, v91
	v_ldexp_f32 v91, v74, v72
	v_ldexp_f32 v93, v75, v72
	v_pk_add_f32 v[72:73], v[90:91], 1.0 op_sel_hi:[1,0]
	v_pk_add_f32 v[94:95], v[90:91], -1.0 op_sel_hi:[1,0]
	v_pk_add_f32 v[74:75], v[72:73], -1.0 op_sel_hi:[1,0]
	v_pk_add_f32 v[96:97], v[94:95], 1.0 op_sel_hi:[1,0]
	v_pk_add_f32 v[74:75], v[90:91], v[74:75] neg_lo:[0,1] neg_hi:[0,1]
	v_pk_add_f32 v[90:91], v[90:91], v[96:97] neg_lo:[0,1] neg_hi:[0,1]
	v_pk_add_f32 v[74:75], v[92:93], v[74:75]
	v_pk_add_f32 v[90:91], v[92:93], v[90:91]
	v_pk_add_f32 v[76:77], v[72:73], v[74:75]
	v_pk_add_f32 v[92:93], v[94:95], v[90:91]
	v_rcp_f32_e32 v78, v76
	v_rcp_f32_e32 v79, v77
	v_pk_add_f32 v[72:73], v[76:77], v[72:73] neg_lo:[0,1] neg_hi:[0,1]
	v_pk_add_f32 v[94:95], v[92:93], v[94:95] neg_lo:[0,1] neg_hi:[0,1]
	v_pk_add_f32 v[72:73], v[74:75], v[72:73] neg_lo:[0,1] neg_hi:[0,1]
	v_pk_mul_f32 v[74:75], v[92:93], v[78:79]
	v_pk_add_f32 v[90:91], v[90:91], v[94:95] neg_lo:[0,1] neg_hi:[0,1]
	v_pk_mul_f32 v[94:95], v[76:77], v[74:75]
	v_cmp_neq_f32_e32 vcc, s64, v108
	v_pk_fma_f32 v[96:97], v[74:75], v[76:77], v[94:95] neg_lo:[0,0,1] neg_hi:[0,0,1]
	s_nop 0
	v_pk_fma_f32 v[96:97], v[74:75], v[72:73], v[96:97]
	s_nop 0
	v_pk_add_f32 v[98:99], v[94:95], v[96:97]
	s_nop 0
	v_pk_add_f32 v[100:101], v[92:93], v[98:99] neg_lo:[0,1] neg_hi:[0,1]
	v_pk_add_f32 v[94:95], v[98:99], v[94:95] neg_lo:[0,1] neg_hi:[0,1]
	v_pk_add_f32 v[92:93], v[92:93], v[100:101] neg_lo:[0,1] neg_hi:[0,1]
	s_nop 0
	v_pk_add_f32 v[92:93], v[92:93], v[98:99] neg_lo:[0,1] neg_hi:[0,1]
	s_nop 0
	v_pk_add_f32 v[90:91], v[90:91], v[92:93]
	v_pk_add_f32 v[92:93], v[94:95], v[96:97] neg_lo:[0,1] neg_hi:[0,1]
	s_nop 0
	v_pk_add_f32 v[90:91], v[92:93], v[90:91]
	s_nop 0
	v_pk_add_f32 v[92:93], v[100:101], v[90:91]
	s_nop 0
	v_pk_mul_f32 v[94:95], v[78:79], v[92:93]
	s_nop 0
	v_pk_mul_f32 v[96:97], v[76:77], v[94:95]
	s_nop 0
	v_pk_fma_f32 v[76:77], v[94:95], v[76:77], v[96:97] neg_lo:[0,0,1] neg_hi:[0,0,1]
	s_nop 0
	v_pk_fma_f32 v[72:73], v[94:95], v[72:73], v[76:77]
	v_pk_add_f32 v[76:77], v[100:101], v[92:93] neg_lo:[0,1] neg_hi:[0,1]
	s_nop 0
	v_pk_add_f32 v[76:77], v[90:91], v[76:77]
	v_pk_add_f32 v[90:91], v[96:97], v[72:73]
	s_nop 0
	v_pk_add_f32 v[98:99], v[92:93], v[90:91] neg_lo:[0,1] neg_hi:[0,1]
	v_pk_add_f32 v[96:97], v[90:91], v[96:97] neg_lo:[0,1] neg_hi:[0,1]
	v_pk_add_f32 v[92:93], v[92:93], v[98:99] neg_lo:[0,1] neg_hi:[0,1]
	v_pk_add_f32 v[72:73], v[96:97], v[72:73] neg_lo:[0,1] neg_hi:[0,1]
	v_pk_add_f32 v[90:91], v[92:93], v[90:91] neg_lo:[0,1] neg_hi:[0,1]
	s_nop 0
	v_pk_add_f32 v[76:77], v[76:77], v[90:91]
	v_cvt_f32_i32_e32 v91, v103
	v_pk_add_f32 v[72:73], v[72:73], v[76:77]
	v_pk_add_f32 v[76:77], v[74:75], v[94:95]
	v_pk_add_f32 v[72:73], v[98:99], v[72:73]
	v_pk_add_f32 v[74:75], v[76:77], v[74:75] neg_lo:[0,1] neg_hi:[0,1]
	v_pk_mul_f32 v[72:73], v[78:79], v[72:73]
	v_pk_add_f32 v[74:75], v[94:95], v[74:75] neg_lo:[0,1] neg_hi:[0,1]
	v_cvt_f32_i32_e32 v90, v102
	v_pk_add_f32 v[72:73], v[74:75], v[72:73]
	s_nop 0
	v_pk_add_f32 v[74:75], v[76:77], v[72:73]
	s_nop 0
	v_pk_mul_f32 v[78:79], v[74:75], v[74:75]
	v_pk_add_f32 v[76:77], v[74:75], v[76:77] neg_lo:[0,1] neg_hi:[0,1]
	v_pk_fma_f32 v[88:89], v[78:79], s[46:47], v[88:89] op_sel_hi:[1,0,0]
	v_pk_add_f32 v[72:73], v[72:73], v[76:77] neg_lo:[0,1] neg_hi:[0,1]
	v_ldexp_f32 v76, v74, 1
	v_pk_fma_f32 v[88:89], v[78:79], v[88:89], s[48:49] op_sel_hi:[1,1,0]
	v_ldexp_f32 v77, v75, 1
	v_pk_mul_f32 v[74:75], v[74:75], v[78:79]
	v_pk_mul_f32 v[78:79], v[90:91], s[50:51] op_sel_hi:[1,0]
	v_pk_mul_f32 v[74:75], v[74:75], v[88:89]
	v_pk_fma_f32 v[94:95], v[90:91], s[50:51], v[78:79] op_sel_hi:[1,0,1] neg_lo:[0,0,1] neg_hi:[0,0,1]
	v_pk_add_f32 v[88:89], v[76:77], v[74:75]
	v_ldexp_f32 v93, v73, 1
	v_pk_add_f32 v[76:77], v[88:89], v[76:77] neg_lo:[0,1] neg_hi:[0,1]
	v_pk_fma_f32 v[90:91], v[90:91], s[52:53], v[94:95] op_sel_hi:[1,0,1]
	v_pk_add_f32 v[74:75], v[74:75], v[76:77] neg_lo:[0,1] neg_hi:[0,1]
	v_ldexp_f32 v72, v72, 1
	v_mov_b32_e32 v76, v78
	v_mov_b32_e32 v77, v75
	v_mov_b32_e32 v92, v90
	v_mov_b32_e32 v73, v93
	v_pk_add_f32 v[76:77], v[76:77], v[92:93]
	v_pk_add_f32 v[92:93], v[72:73], v[74:75]
	v_mov_b32_e32 v75, v89
	v_mov_b32_e32 v73, v93
	v_pk_add_f32 v[94:95], v[78:79], v[90:91]
	v_pk_add_f32 v[72:73], v[72:73], v[74:75]
	v_pk_add_f32 v[74:75], v[88:89], v[92:93]
	v_mov_b32_e32 v104, v88
	v_pk_add_f32 v[96:97], v[94:95], v[74:75]
	v_mov_b32_e32 v102, v74
	v_mov_b32_e32 v103, v97
	v_mov_b32_e32 v105, v95
	v_pk_add_f32 v[102:103], v[102:103], v[104:105] neg_lo:[0,1] neg_hi:[0,1]
	v_mov_b32_e32 v98, v96
	v_mov_b32_e32 v99, v95
	v_mov_b32_e32 v100, v94
	v_mov_b32_e32 v101, v79
	v_mov_b32_e32 v104, v94
	v_mov_b32_e32 v105, v97
	v_mov_b32_e32 v79, v103
	v_pk_add_f32 v[98:99], v[98:99], v[100:101] neg_lo:[0,1] neg_hi:[0,1]
	v_mov_b32_e32 v100, v74
	v_mov_b32_e32 v101, v91
	v_pk_add_f32 v[78:79], v[104:105], v[78:79] neg_lo:[0,1] neg_hi:[0,1]
	v_pk_add_f32 v[100:101], v[100:101], v[98:99] neg_lo:[0,1] neg_hi:[0,1]
	v_mov_b32_e32 v104, v78
	v_mov_b32_e32 v105, v99
	v_mov_b32_e32 v106, v96
	v_mov_b32_e32 v107, v75
	v_mov_b32_e32 v99, v89
	v_pk_add_f32 v[104:105], v[90:91], v[104:105] neg_lo:[0,1] neg_hi:[0,1]
	v_pk_add_f32 v[98:99], v[106:107], v[98:99] neg_lo:[0,1] neg_hi:[0,1]
	v_mov_b32_e32 v91, v95
	v_pk_add_f32 v[76:77], v[76:77], v[98:99] neg_lo:[0,1] neg_hi:[0,1]
	v_pk_add_f32 v[78:79], v[90:91], v[78:79] neg_lo:[0,1] neg_hi:[0,1]
	v_pk_add_f32 v[72:73], v[72:73], v[102:103] neg_lo:[0,1] neg_hi:[0,1]
	v_pk_add_f32 v[74:75], v[74:75], v[88:89] neg_lo:[0,1] neg_hi:[0,1]
	v_pk_add_f32 v[88:89], v[72:73], v[78:79]
	v_mov_b32_e32 v79, v101
	v_mov_b32_e32 v73, v77
	v_pk_add_f32 v[90:91], v[100:101], v[76:77]
	v_pk_add_f32 v[72:73], v[78:79], v[72:73]
	v_mov_b32_e32 v76, v88
	v_pk_add_f32 v[72:73], v[72:73], v[104:105] neg_lo:[0,1] neg_hi:[0,1]
	v_mov_b32_e32 v77, v91
	v_pk_add_f32 v[74:75], v[92:93], v[74:75] neg_lo:[0,1] neg_hi:[0,1]
	v_pk_add_f32 v[76:77], v[76:77], v[72:73] neg_lo:[0,1] neg_hi:[0,1]
	v_pk_add_f32 v[72:73], v[74:75], v[72:73] neg_lo:[0,1] neg_hi:[0,1]
	v_pk_add_f32 v[76:77], v[78:79], v[76:77] neg_lo:[0,1] neg_hi:[0,1]
	v_pk_add_f32 v[74:75], v[90:91], v[88:89]
	v_pk_add_f32 v[72:73], v[72:73], v[76:77]
	v_pk_add_f32 v[76:77], v[96:97], v[74:75]
	s_nop 0
	v_pk_add_f32 v[78:79], v[76:77], v[96:97] neg_lo:[0,1] neg_hi:[0,1]
	s_nop 0
	v_pk_add_f32 v[74:75], v[74:75], v[78:79] neg_lo:[0,1] neg_hi:[0,1]
	s_nop 0
	v_pk_add_f32 v[72:73], v[72:73], v[74:75]
	s_nop 0
	v_pk_add_f32 v[72:73], v[76:77], v[72:73]
	s_nop 0
	v_cndmask_b32_e32 v72, v200, v72, vcc
	v_cmp_neq_f32_e32 vcc, s64, v109
	s_nop 1
	v_cndmask_b32_e32 v73, v200, v73, vcc
	v_cmp_ngt_f32_e32 vcc, -1.0, v109
	s_nop 1
	v_cndmask_b32_e32 v73, v201, v73, vcc
	v_cmp_ngt_f32_e32 vcc, -1.0, v108
	s_nop 1
	v_cndmask_b32_e32 v72, v201, v72, vcc
	v_cmp_neq_f32_e32 vcc, -1.0, v108
	s_nop 1
	v_cndmask_b32_e32 v72, v202, v72, vcc
	v_cmp_neq_f32_e32 vcc, -1.0, v109
	s_nop 1
	v_cndmask_b32_e32 v73, v202, v73, vcc
	v_cmp_lt_f32_e64 vcc, |v109|, s65
	s_nop 1
	v_cndmask_b32_e32 v73, v73, v109, vcc
	v_cmp_lt_f32_e64 vcc, |v108|, s65
	s_nop 1
	v_cndmask_b32_e32 v72, v72, v108, vcc
	v_pk_add_f32 v[66:67], v[66:67], v[72:73] neg_lo:[0,1] neg_hi:[0,1]
	global_store_dwordx4 v199, v[68:71], s[56:57] offset:64
	global_store_dwordx4 v199, v[64:67], s[56:57] offset:80

.LBB0_288:
	s_or_b64 exec, exec, s[0:1]
	global_load_dwordx4 v[84:87], v[140:141], off
	ds_read_b128 v[88:91], v230 offset:3072
	ds_read_b128 v[92:95], v230 offset:2048
	ds_read_b128 v[96:99], v230 offset:1024
	ds_read_b128 v[100:103], v230
	v_mul_f32_e32 v76, v76, v82
	v_mul_f32_e32 v74, v74, v82
	v_mul_f32_e32 v72, v72, v82
	v_mul_f32_e32 v70, v70, v82
	v_mul_f32_e32 v66, v66, v82
	v_mul_f32_e32 v64, v64, v82
	v_mul_f32_e32 v68, v68, v82
	v_mul_f32_e32 v80, v80, v82
	s_waitcnt vmcnt(0)
	v_mul_f32_e32 v76, v76, v84
	v_mul_f32_e32 v74, v74, v86
	s_waitcnt vmcnt(0)
	s_waitcnt lgkmcnt(1)
	v_pk_fma_f32 v[98:99], v[98:99], v[76:77], 0 op_sel_hi:[1,0,0]
	s_waitcnt vmcnt(0)
	s_waitcnt lgkmcnt(0)
	v_pk_fma_f32 v[78:79], v[102:103], v[76:77], 0 op_sel_hi:[1,0,0]
	v_pk_fma_f32 v[100:101], v[100:101], v[76:77], 0 op_sel_hi:[1,0,0]
	v_pk_fma_f32 v[96:97], v[96:97], v[76:77], 0 op_sel_hi:[1,0,0]
	v_mul_f32_e32 v76, v77, v82
	v_mul_f32_e32 v76, v76, v85
	v_pk_fma_f32 v[84:85], v[94:95], v[76:77], v[78:79] op_sel_hi:[1,0,1]
	v_pk_fma_f32 v[100:101], v[92:93], v[76:77], v[100:101] op_sel_hi:[1,0,1]
	v_pk_fma_f32 v[102:103], v[76:77], v[90:91], v[98:99] op_sel_hi:[0,1,1]
	v_pk_fma_f32 v[104:105], v[76:77], v[88:89], v[96:97] op_sel_hi:[0,1,1]
	ds_read_b128 v[76:79], v230 offset:19456
	ds_read_b128 v[88:91], v230 offset:18432
	ds_read_b128 v[92:95], v230 offset:17408
	ds_read_b128 v[96:99], v230 offset:16384
	s_waitcnt vmcnt(0)
	s_waitcnt lgkmcnt(1)
	v_pk_fma_f32 v[92:93], v[74:75], v[92:93], v[104:105] op_sel_hi:[0,1,1]
	s_waitcnt vmcnt(0)
	s_waitcnt lgkmcnt(0)
	v_pk_fma_f32 v[96:97], v[74:75], v[96:97], v[100:101] op_sel_hi:[0,1,1]
	v_pk_fma_f32 v[84:85], v[74:75], v[98:99], v[84:85] op_sel_hi:[0,1,1]
	v_pk_fma_f32 v[94:95], v[74:75], v[94:95], v[102:103] op_sel_hi:[0,1,1]
	v_mul_f32_e32 v74, v75, v82
	v_mul_f32_e32 v74, v74, v87
	v_pk_fma_f32 v[100:101], v[74:75], v[90:91], v[84:85] op_sel_hi:[0,1,1]
	v_pk_fma_f32 v[102:103], v[74:75], v[88:89], v[96:97] op_sel_hi:[0,1,1]
	v_pk_fma_f32 v[78:79], v[74:75], v[78:79], v[94:95] op_sel_hi:[0,1,1]
	v_pk_fma_f32 v[104:105], v[74:75], v[76:77], v[92:93] op_sel_hi:[0,1,1]
	global_load_dwordx4 v[74:77], v[140:141], off offset:1024
	ds_read_b128 v[84:87], v230 offset:35840
	ds_read_b128 v[88:91], v230 offset:34816
	ds_read_b128 v[92:95], v230 offset:33792
	ds_read_b128 v[96:99], v230 offset:32768
	s_waitcnt vmcnt(0)
	v_mul_f32_e32 v72, v72, v74
	v_mul_f32_e32 v70, v70, v76
	s_waitcnt vmcnt(0)
	s_waitcnt lgkmcnt(1)
	v_pk_fma_f32 v[92:93], v[92:93], v[72:73], v[104:105] op_sel_hi:[1,0,1]
	s_waitcnt vmcnt(0)
	s_waitcnt lgkmcnt(0)
	v_pk_fma_f32 v[96:97], v[96:97], v[72:73], v[102:103] op_sel_hi:[1,0,1]
	v_pk_fma_f32 v[98:99], v[98:99], v[72:73], v[100:101] op_sel_hi:[1,0,1]
	v_pk_fma_f32 v[78:79], v[94:95], v[72:73], v[78:79] op_sel_hi:[1,0,1]
	v_mul_f32_e32 v72, v73, v82
	v_mul_f32_e32 v72, v72, v75
	v_pk_fma_f32 v[98:99], v[90:91], v[72:73], v[98:99] op_sel_hi:[1,0,1]
	v_pk_fma_f32 v[96:97], v[88:89], v[72:73], v[96:97] op_sel_hi:[1,0,1]
	v_pk_fma_f32 v[78:79], v[72:73], v[86:87], v[78:79] op_sel_hi:[0,1,1]
	v_pk_fma_f32 v[100:101], v[72:73], v[84:85], v[92:93] op_sel_hi:[0,1,1]
	ds_read_b128 v[72:75], v230 offset:52224
	ds_read_b128 v[84:87], v230 offset:51200
	ds_read_b128 v[88:91], v230 offset:50176
	ds_read_b128 v[92:95], v230 offset:49152
	s_waitcnt vmcnt(0)
	s_waitcnt lgkmcnt(1)
	v_pk_fma_f32 v[88:89], v[70:71], v[88:89], v[100:101] op_sel_hi:[0,1,1]
	s_waitcnt vmcnt(0)
	s_waitcnt lgkmcnt(0)
	v_pk_fma_f32 v[92:93], v[70:71], v[92:93], v[96:97] op_sel_hi:[0,1,1]
	v_pk_fma_f32 v[94:95], v[70:71], v[94:95], v[98:99] op_sel_hi:[0,1,1]
	v_pk_fma_f32 v[78:79], v[70:71], v[90:91], v[78:79] op_sel_hi:[0,1,1]
	v_mul_f32_e32 v70, v71, v82
	v_mul_f32_e32 v70, v70, v77
	v_pk_fma_f32 v[96:97], v[70:71], v[86:87], v[94:95] op_sel_hi:[0,1,1]
	v_pk_fma_f32 v[98:99], v[70:71], v[84:85], v[92:93] op_sel_hi:[0,1,1]
	v_pk_fma_f32 v[78:79], v[70:71], v[74:75], v[78:79] op_sel_hi:[0,1,1]
	v_pk_fma_f32 v[100:101], v[70:71], v[72:73], v[88:89] op_sel_hi:[0,1,1]
	global_load_dwordx4 v[70:73], v[140:141], off offset:2048
	ds_read_b128 v[74:77], v231 offset:3072
	ds_read_b128 v[84:87], v231 offset:2048
	ds_read_b128 v[88:91], v231 offset:1024
	ds_read_b128 v[92:95], v231
	s_waitcnt vmcnt(0)
	v_mul_f32_e32 v66, v66, v70
	v_mul_f32_e32 v64, v64, v72
	s_waitcnt vmcnt(0)
	s_waitcnt lgkmcnt(1)
	v_pk_fma_f32 v[88:89], v[88:89], v[66:67], v[100:101] op_sel_hi:[1,0,1]
	s_waitcnt vmcnt(0)
	s_waitcnt lgkmcnt(0)
	v_pk_fma_f32 v[92:93], v[92:93], v[66:67], v[98:99] op_sel_hi:[1,0,1]
	v_pk_fma_f32 v[94:95], v[94:95], v[66:67], v[96:97] op_sel_hi:[1,0,1]
	v_pk_fma_f32 v[78:79], v[90:91], v[66:67], v[78:79] op_sel_hi:[1,0,1]
	v_mul_f32_e32 v66, v67, v82
	v_mul_f32_e32 v66, v66, v71
	v_pk_fma_f32 v[70:71], v[86:87], v[66:67], v[94:95] op_sel_hi:[1,0,1]
	v_pk_fma_f32 v[96:97], v[84:85], v[66:67], v[92:93] op_sel_hi:[1,0,1]
	v_pk_fma_f32 v[78:79], v[66:67], v[76:77], v[78:79] op_sel_hi:[0,1,1]
	v_pk_fma_f32 v[66:67], v[66:67], v[74:75], v[88:89] op_sel_hi:[0,1,1]
	ds_read_b128 v[74:77], v231 offset:19456
	ds_read_b128 v[84:87], v231 offset:18432
	ds_read_b128 v[88:91], v231 offset:17408
	ds_read_b128 v[92:95], v231 offset:16384
	s_waitcnt vmcnt(0)
	s_waitcnt lgkmcnt(1)
	v_pk_fma_f32 v[66:67], v[64:65], v[88:89], v[66:67] op_sel_hi:[0,1,1]
	s_waitcnt vmcnt(0)
	s_waitcnt lgkmcnt(0)
	v_pk_fma_f32 v[92:93], v[64:65], v[92:93], v[96:97] op_sel_hi:[0,1,1]
	v_pk_fma_f32 v[70:71], v[64:65], v[94:95], v[70:71] op_sel_hi:[0,1,1]
	v_pk_fma_f32 v[78:79], v[64:65], v[90:91], v[78:79] op_sel_hi:[0,1,1]
	v_mul_f32_e32 v64, v65, v82
	v_mul_f32_e32 v64, v64, v73
	v_pk_fma_f32 v[94:95], v[64:65], v[86:87], v[70:71] op_sel_hi:[0,1,1]
	v_pk_fma_f32 v[92:93], v[64:65], v[84:85], v[92:93] op_sel_hi:[0,1,1]
	v_pk_fma_f32 v[78:79], v[64:65], v[76:77], v[78:79] op_sel_hi:[0,1,1]
	v_pk_fma_f32 v[96:97], v[64:65], v[74:75], v[66:67] op_sel_hi:[0,1,1]
	global_load_dwordx4 v[64:67], v[140:141], off offset:3072
	ds_read_b128 v[70:73], v231 offset:35840
	ds_read_b128 v[74:77], v231 offset:34816
	ds_read_b128 v[84:87], v231 offset:33792
	ds_read_b128 v[88:91], v231 offset:32768
	s_waitcnt vmcnt(0)
	v_mul_f32_e32 v64, v68, v64
	v_mul_f32_e32 v66, v80, v66
	s_waitcnt vmcnt(0)
	s_waitcnt lgkmcnt(1)
	v_pk_fma_f32 v[84:85], v[84:85], v[64:65], v[96:97] op_sel_hi:[1,0,1]
	s_waitcnt vmcnt(0)
	s_waitcnt lgkmcnt(0)
	v_pk_fma_f32 v[88:89], v[88:89], v[64:65], v[92:93] op_sel_hi:[1,0,1]
	v_pk_fma_f32 v[90:91], v[90:91], v[64:65], v[94:95] op_sel_hi:[1,0,1]
	v_pk_fma_f32 v[78:79], v[86:87], v[64:65], v[78:79] op_sel_hi:[1,0,1]
	v_mul_f32_e32 v64, v69, v82
	v_mul_f32_e32 v68, v64, v65
	v_pk_fma_f32 v[86:87], v[76:77], v[68:69], v[90:91] op_sel_hi:[1,0,1]
	v_pk_fma_f32 v[88:89], v[74:75], v[68:69], v[88:89] op_sel_hi:[1,0,1]
	v_pk_fma_f32 v[64:65], v[68:69], v[72:73], v[78:79] op_sel_hi:[0,1,1]
	v_pk_fma_f32 v[84:85], v[68:69], v[70:71], v[84:85] op_sel_hi:[0,1,1]
	ds_read_b128 v[68:71], v231 offset:52224
	ds_read_b128 v[72:75], v231 offset:51200
	ds_read_b128 v[76:79], v231 offset:50176
	ds_read_b128 v[90:93], v231 offset:49152
	s_waitcnt vmcnt(0)
	s_waitcnt lgkmcnt(1)
	v_pk_fma_f32 v[76:77], v[66:67], v[76:77], v[84:85] op_sel_hi:[0,1,1]
	s_waitcnt vmcnt(0)
	s_waitcnt lgkmcnt(0)
	v_pk_fma_f32 v[88:89], v[66:67], v[90:91], v[88:89] op_sel_hi:[0,1,1]
	v_pk_fma_f32 v[86:87], v[66:67], v[92:93], v[86:87] op_sel_hi:[0,1,1]
	v_pk_fma_f32 v[64:65], v[66:67], v[78:79], v[64:65] op_sel_hi:[0,1,1]
	v_mul_f32_e32 v66, v81, v82
	v_mul_f32_e32 v78, v66, v67
	v_pk_fma_f32 v[64:65], v[78:79], v[70:71], v[64:65] op_sel_hi:[0,1,1]
	v_pk_fma_f32 v[70:71], v[78:79], v[68:69], v[76:77] op_sel_hi:[0,1,1]
	ds_bpermute_b32 v77, v190, v64
	ds_bpermute_b32 v68, v190, v70
	v_pk_fma_f32 v[66:67], v[78:79], v[74:75], v[86:87] op_sel_hi:[0,1,1]
	v_pk_fma_f32 v[72:73], v[78:79], v[72:73], v[88:89] op_sel_hi:[0,1,1]
	ds_bpermute_b32 v74, v190, v72
	s_waitcnt lgkmcnt(2)
	v_add_f32_e32 v64, v64, v77
	ds_bpermute_b32 v77, v191, v64
	s_waitcnt lgkmcnt(2)
	v_add_f32_e32 v68, v70, v68
	ds_bpermute_b32 v75, v190, v73
	ds_bpermute_b32 v70, v190, v71
	ds_bpermute_b32 v76, v190, v66
	s_waitcnt lgkmcnt(3)
	v_add_f32_e32 v64, v64, v77
	ds_bpermute_b32 v77, v192, v64
	s_waitcnt lgkmcnt(3)
	v_pk_add_f32 v[72:73], v[72:73], v[74:75]
	s_waitcnt lgkmcnt(2)
	v_add_f32_e32 v70, v71, v70
	ds_bpermute_b32 v69, v191, v68
	ds_bpermute_b32 v74, v191, v72
	s_waitcnt lgkmcnt(2)
	v_add_f32_e32 v64, v64, v77
	ds_bpermute_b32 v77, v193, v64
	ds_bpermute_b32 v75, v191, v73
	ds_bpermute_b32 v71, v191, v70
	s_waitcnt lgkmcnt(4)
	v_add_f32_e32 v68, v68, v69
	ds_bpermute_b32 v69, v192, v68
	s_waitcnt lgkmcnt(3)
	v_add_f32_e32 v64, v64, v77
	ds_bpermute_b32 v77, v194, v64
	s_waitcnt lgkmcnt(3)
	v_pk_add_f32 v[72:73], v[72:73], v[74:75]
	s_waitcnt lgkmcnt(2)
	v_add_f32_e32 v70, v70, v71
	ds_bpermute_b32 v74, v192, v72
	ds_bpermute_b32 v75, v192, v73
	s_waitcnt lgkmcnt(2)
	v_add_f32_e32 v80, v64, v77
	ds_bpermute_b32 v77, v190, v67
	ds_bpermute_b32 v64, v190, v65
	ds_bpermute_b32 v71, v192, v70
	v_add_f32_e32 v68, v68, v69
	s_waitcnt lgkmcnt(3)
	v_pk_add_f32 v[72:73], v[72:73], v[74:75]
	s_waitcnt lgkmcnt(2)
	v_pk_add_f32 v[66:67], v[66:67], v[76:77]
	s_waitcnt lgkmcnt(1)
	v_add_f32_e32 v64, v65, v64
	ds_bpermute_b32 v76, v191, v66
	ds_bpermute_b32 v77, v191, v67
	ds_bpermute_b32 v65, v191, v64
	s_waitcnt lgkmcnt(3)
	v_add_f32_e32 v70, v70, v71
	ds_bpermute_b32 v69, v193, v68
	ds_bpermute_b32 v74, v193, v72
	s_waitcnt lgkmcnt(3)
	v_pk_add_f32 v[66:67], v[66:67], v[76:77]
	s_waitcnt lgkmcnt(2)
	v_add_f32_e32 v64, v64, v65
	ds_bpermute_b32 v76, v192, v66
	ds_bpermute_b32 v77, v192, v67
	ds_bpermute_b32 v65, v192, v64
	ds_bpermute_b32 v75, v193, v73
	ds_bpermute_b32 v71, v193, v70
	s_waitcnt lgkmcnt(6)
	v_add_f32_e32 v68, v68, v69
	s_waitcnt lgkmcnt(3)
	v_pk_add_f32 v[66:67], v[66:67], v[76:77]
	s_waitcnt lgkmcnt(2)
	v_add_f32_e32 v64, v64, v65
	ds_bpermute_b32 v76, v193, v66
	ds_bpermute_b32 v77, v193, v67
	ds_bpermute_b32 v65, v193, v64
	s_waitcnt lgkmcnt(4)
	v_pk_add_f32 v[72:73], v[72:73], v[74:75]
	s_waitcnt lgkmcnt(3)
	v_add_f32_e32 v70, v70, v71
	ds_bpermute_b32 v69, v194, v68
	s_waitcnt lgkmcnt(2)
	v_pk_add_f32 v[66:67], v[66:67], v[76:77]
	s_waitcnt lgkmcnt(1)
	v_add_f32_e32 v64, v64, v65
	ds_bpermute_b32 v74, v194, v72
	ds_bpermute_b32 v75, v194, v73
	ds_bpermute_b32 v71, v194, v70
	ds_bpermute_b32 v76, v194, v66
	ds_bpermute_b32 v77, v194, v67
	ds_bpermute_b32 v65, v194, v64
	s_waitcnt lgkmcnt(6)
	v_add_f32_e32 v68, v68, v69
	s_waitcnt lgkmcnt(4)
	v_pk_add_f32 v[72:73], v[72:73], v[74:75]
	s_waitcnt lgkmcnt(3)
	v_add_f32_e32 v70, v70, v71
	s_waitcnt lgkmcnt(1)
	v_pk_add_f32 v[76:77], v[66:67], v[76:77]
	s_waitcnt lgkmcnt(0)
	v_add_f32_e32 v82, v64, v65
	ds_bpermute_b32 v69, v195, v68
	ds_bpermute_b32 v74, v195, v72
	ds_bpermute_b32 v75, v195, v73
	ds_bpermute_b32 v71, v195, v70
	ds_bpermute_b32 v81, v195, v80
	ds_bpermute_b32 v78, v195, v76
	ds_bpermute_b32 v79, v195, v77
	ds_bpermute_b32 v83, v195, v82
	s_and_saveexec_b64 s[0:1], s[4:5]
	s_cbranch_execz .LBB0_261
	global_load_dwordx4 v[64:67], v129, s[20:21] offset:16
	s_waitcnt lgkmcnt(0)
	v_add_f32_e32 v120, v82, v83
	v_add_f32_e32 v82, v68, v69
	v_add_f32_e32 v83, v70, v71
	global_load_dwordx4 v[68:71], v129, s[20:21]
	v_add_f32_e32 v121, v80, v81
	v_mov_b64_e32 v[80:81], s[44:45]
	v_pk_add_f32 v[72:73], v[72:73], v[74:75]
	v_pk_add_f32 v[76:77], v[76:77], v[78:79]
	s_lshl_b64 s[10:11], s[54:55], 5
	s_add_u32 s10, s53, s10
	s_addc_u32 s11, s58, s11
	s_waitcnt vmcnt(1)
	v_add_f32_e32 v64, v82, v64
	v_mul_f32_e64 v82, |v64|, s62
	v_add_f32_e32 v65, v83, v65
	v_exp_f32_e32 v122, v82
	v_mul_f32_e64 v83, |v65|, s62
	v_exp_f32_e32 v123, v83
	v_add_f32_e32 v66, v121, v66
	v_add_f32_e32 v86, 1.0, v122
	v_frexp_mant_f32_e32 v89, v86
	v_cvt_f64_f32_e32 v[82:83], v86
	v_add_f32_e32 v87, 1.0, v123
	v_frexp_exp_i32_f64_e32 v82, v[82:83]
	v_cmp_gt_f32_e32 vcc, s63, v89
	v_add_f32_e32 v88, -1.0, v86
	v_add_f32_e32 v90, -1.0, v87
	v_frexp_mant_f32_e32 v91, v87
	v_cvt_f64_f32_e32 v[84:85], v87
	v_subbrev_co_u32_e32 v82, vcc, 0, v82, vcc
	v_sub_f32_e32 v92, v88, v86
	v_sub_f32_e32 v83, v90, v87
	v_frexp_exp_i32_f64_e32 v84, v[84:85]
	v_cmp_gt_f32_e32 vcc, s63, v91
	v_sub_f32_e32 v88, v122, v88
	v_sub_f32_e32 v90, v123, v90
	v_add_f32_e32 v85, 1.0, v92
	v_add_f32_e32 v83, 1.0, v83
	v_subbrev_co_u32_e32 v84, vcc, 0, v84, vcc
	v_add_f32_e32 v85, v88, v85
	v_sub_u32_e32 v88, 0, v82
	v_add_f32_e32 v89, v90, v83
	v_sub_u32_e32 v90, 0, v84
	v_cvt_f32_i32_e32 v83, v84
	v_cvt_f32_i32_e32 v82, v82
	v_ldexp_f32 v84, v86, v88
	v_ldexp_f32 v86, v85, v88
	v_ldexp_f32 v85, v87, v90
	v_ldexp_f32 v87, v89, v90
	v_pk_add_f32 v[88:89], v[84:85], 1.0 op_sel_hi:[1,0]
	v_pk_add_f32 v[90:91], v[84:85], -1.0 op_sel_hi:[1,0]
	v_pk_add_f32 v[92:93], v[88:89], -1.0 op_sel_hi:[1,0]
	v_pk_add_f32 v[94:95], v[90:91], 1.0 op_sel_hi:[1,0]
	v_pk_add_f32 v[92:93], v[84:85], v[92:93] neg_lo:[0,1] neg_hi:[0,1]
	v_pk_add_f32 v[84:85], v[84:85], v[94:95] neg_lo:[0,1] neg_hi:[0,1]
	v_pk_mul_f32 v[94:95], v[82:83], s[50:51] op_sel_hi:[1,0]
	v_pk_add_f32 v[92:93], v[86:87], v[92:93]
	v_pk_add_f32 v[84:85], v[86:87], v[84:85]
	v_pk_fma_f32 v[86:87], v[82:83], s[50:51], v[94:95] op_sel_hi:[1,0,1] neg_lo:[0,0,1] neg_hi:[0,0,1]
	v_pk_add_f32 v[100:101], v[88:89], v[92:93]
	v_pk_fma_f32 v[82:83], v[82:83], s[52:53], v[86:87] op_sel_hi:[1,0,1]
	v_rcp_f32_e32 v86, v100
	v_rcp_f32_e32 v87, v101
	v_pk_add_f32 v[102:103], v[90:91], v[84:85]
	v_pk_add_f32 v[88:89], v[100:101], v[88:89] neg_lo:[0,1] neg_hi:[0,1]
	v_pk_add_f32 v[90:91], v[102:103], v[90:91] neg_lo:[0,1] neg_hi:[0,1]
	v_pk_mul_f32 v[110:111], v[102:103], v[86:87]
	v_pk_add_f32 v[88:89], v[92:93], v[88:89] neg_lo:[0,1] neg_hi:[0,1]
	v_pk_mul_f32 v[112:113], v[100:101], v[110:111]
	v_pk_add_f32 v[84:85], v[84:85], v[90:91] neg_lo:[0,1] neg_hi:[0,1]
	v_pk_fma_f32 v[114:115], v[110:111], v[100:101], v[112:113] neg_lo:[0,0,1] neg_hi:[0,0,1]
	v_pk_add_f32 v[104:105], v[94:95], v[82:83]
	v_pk_fma_f32 v[114:115], v[110:111], v[88:89], v[114:115]
	v_mov_b32_e32 v96, v94
	v_pk_add_f32 v[116:117], v[112:113], v[114:115]
	v_mov_b32_e32 v106, v82
	v_pk_add_f32 v[118:119], v[102:103], v[116:117] neg_lo:[0,1] neg_hi:[0,1]
	v_pk_add_f32 v[112:113], v[116:117], v[112:113] neg_lo:[0,1] neg_hi:[0,1]
	v_pk_add_f32 v[102:103], v[102:103], v[118:119] neg_lo:[0,1] neg_hi:[0,1]
	v_pk_add_f32 v[112:113], v[112:113], v[114:115] neg_lo:[0,1] neg_hi:[0,1]
	v_pk_add_f32 v[102:103], v[102:103], v[116:117] neg_lo:[0,1] neg_hi:[0,1]
	v_mov_b32_e32 v93, v105
	v_pk_add_f32 v[84:85], v[84:85], v[102:103]
	v_mov_b32_e32 v99, v95
	v_pk_add_f32 v[84:85], v[112:113], v[84:85]
	v_mov_b32_e32 v91, v105
	v_pk_add_f32 v[102:103], v[118:119], v[84:85]
	v_mov_b32_e32 v98, v104
	v_pk_mul_f32 v[112:113], v[86:87], v[102:103]
	v_pk_add_f32 v[114:115], v[118:119], v[102:103] neg_lo:[0,1] neg_hi:[0,1]
	v_pk_mul_f32 v[116:117], v[100:101], v[112:113]
	v_pk_add_f32 v[84:85], v[84:85], v[114:115]
	v_pk_add_f32 v[114:115], v[110:111], v[112:113]
	v_pk_fma_f32 v[100:101], v[112:113], v[100:101], v[116:117] neg_lo:[0,0,1] neg_hi:[0,0,1]
	v_pk_add_f32 v[110:111], v[114:115], v[110:111] neg_lo:[0,1] neg_hi:[0,1]
	v_pk_fma_f32 v[88:89], v[112:113], v[88:89], v[100:101]
	v_pk_add_f32 v[100:101], v[112:113], v[110:111] neg_lo:[0,1] neg_hi:[0,1]
	v_pk_add_f32 v[110:111], v[116:117], v[88:89]
	v_mov_b32_e32 v109, v83
	v_pk_add_f32 v[112:113], v[110:111], v[116:117] neg_lo:[0,1] neg_hi:[0,1]
	v_pk_add_f32 v[116:117], v[102:103], v[110:111] neg_lo:[0,1] neg_hi:[0,1]
	v_pk_add_f32 v[88:89], v[112:113], v[88:89] neg_lo:[0,1] neg_hi:[0,1]
	v_pk_add_f32 v[102:103], v[102:103], v[116:117] neg_lo:[0,1] neg_hi:[0,1]
	v_cmp_neq_f32_e32 vcc, s64, v122
	v_pk_add_f32 v[102:103], v[102:103], v[110:111] neg_lo:[0,1] neg_hi:[0,1]
	v_add_f32_e32 v67, v120, v67
	v_pk_add_f32 v[84:85], v[84:85], v[102:103]
	v_mul_f32_e64 v74, |v67|, s62
	v_pk_add_f32 v[84:85], v[88:89], v[84:85]
	v_min_f32_e32 v64, 0, v64
	v_pk_add_f32 v[84:85], v[116:117], v[84:85]
	v_min_f32_e32 v65, 0, v65
	v_pk_mul_f32 v[84:85], v[86:87], v[84:85]
	s_waitcnt vmcnt(0)
	v_pk_add_f32 v[68:69], v[72:73], v[68:69]
	v_pk_add_f32 v[84:85], v[100:101], v[84:85]
	v_pk_add_f32 v[70:71], v[76:77], v[70:71]
	v_pk_add_f32 v[86:87], v[114:115], v[84:85]
	v_min_f32_e32 v67, 0, v67
	v_pk_add_f32 v[88:89], v[86:87], v[114:115] neg_lo:[0,1] neg_hi:[0,1]
	v_pk_mul_f32 v[102:103], v[86:87], v[86:87]
	v_pk_add_f32 v[84:85], v[84:85], v[88:89] neg_lo:[0,1] neg_hi:[0,1]
	v_pk_fma_f32 v[88:89], v[102:103], s[46:47], v[80:81] op_sel_hi:[1,0,0]
	v_ldexp_f32 v100, v86, 1
	v_ldexp_f32 v101, v87, 1
	v_pk_mul_f32 v[86:87], v[86:87], v[102:103]
	v_pk_fma_f32 v[88:89], v[102:103], v[88:89], s[48:49] op_sel_hi:[1,1,0]
	v_ldexp_f32 v107, v85, 1
	v_pk_mul_f32 v[86:87], v[86:87], v[88:89]
	v_ldexp_f32 v84, v84, 1
	v_pk_add_f32 v[88:89], v[100:101], v[86:87]
	v_mov_b32_e32 v85, v107
	v_pk_add_f32 v[100:101], v[88:89], v[100:101] neg_lo:[0,1] neg_hi:[0,1]
	v_mov_b32_e32 v92, v88
	v_pk_add_f32 v[86:87], v[86:87], v[100:101] neg_lo:[0,1] neg_hi:[0,1]
	s_nop 0
	v_pk_add_f32 v[100:101], v[84:85], v[86:87]
	v_mov_b32_e32 v97, v87
	v_mov_b32_e32 v87, v89
	v_mov_b32_e32 v85, v101
	v_pk_add_f32 v[102:103], v[88:89], v[100:101]
	v_pk_add_f32 v[84:85], v[84:85], v[86:87]
	v_pk_add_f32 v[86:87], v[104:105], v[102:103]
	v_pk_add_f32 v[96:97], v[96:97], v[106:107]
	v_mov_b32_e32 v106, v102
	v_mov_b32_e32 v107, v87
	v_pk_add_f32 v[92:93], v[106:107], v[92:93] neg_lo:[0,1] neg_hi:[0,1]
	v_mov_b32_e32 v90, v86
	v_mov_b32_e32 v106, v104
	v_mov_b32_e32 v95, v93
	v_mov_b32_e32 v108, v102
	v_pk_add_f32 v[90:91], v[90:91], v[98:99] neg_lo:[0,1] neg_hi:[0,1]
	v_pk_add_f32 v[94:95], v[106:107], v[94:95] neg_lo:[0,1] neg_hi:[0,1]
	v_pk_add_f32 v[98:99], v[108:109], v[90:91] neg_lo:[0,1] neg_hi:[0,1]
	v_mov_b32_e32 v106, v94
	v_mov_b32_e32 v107, v91
	v_mov_b32_e32 v108, v86
	v_mov_b32_e32 v109, v103
	v_mov_b32_e32 v91, v89
	v_pk_add_f32 v[106:107], v[82:83], v[106:107] neg_lo:[0,1] neg_hi:[0,1]
	v_pk_add_f32 v[90:91], v[108:109], v[90:91] neg_lo:[0,1] neg_hi:[0,1]
	v_mov_b32_e32 v83, v105
	v_pk_add_f32 v[90:91], v[96:97], v[90:91] neg_lo:[0,1] neg_hi:[0,1]
	v_pk_add_f32 v[82:83], v[82:83], v[94:95] neg_lo:[0,1] neg_hi:[0,1]
	v_pk_add_f32 v[84:85], v[84:85], v[92:93] neg_lo:[0,1] neg_hi:[0,1]
	v_pk_add_f32 v[94:95], v[98:99], v[90:91]
	v_pk_add_f32 v[92:93], v[84:85], v[82:83]
	v_mov_b32_e32 v83, v99
	v_mov_b32_e32 v85, v91
	v_pk_add_f32 v[84:85], v[82:83], v[84:85]
	v_pk_add_f32 v[88:89], v[102:103], v[88:89] neg_lo:[0,1] neg_hi:[0,1]
	v_pk_add_f32 v[84:85], v[84:85], v[106:107] neg_lo:[0,1] neg_hi:[0,1]
	v_mov_b32_e32 v90, v92
	v_mov_b32_e32 v91, v95
	v_pk_add_f32 v[88:89], v[100:101], v[88:89] neg_lo:[0,1] neg_hi:[0,1]
	v_pk_add_f32 v[90:91], v[90:91], v[84:85] neg_lo:[0,1] neg_hi:[0,1]
	v_pk_add_f32 v[84:85], v[88:89], v[84:85] neg_lo:[0,1] neg_hi:[0,1]
	v_pk_add_f32 v[82:83], v[82:83], v[90:91] neg_lo:[0,1] neg_hi:[0,1]
	v_exp_f32_e32 v101, v74
	v_pk_add_f32 v[82:83], v[84:85], v[82:83]
	v_pk_add_f32 v[84:85], v[94:95], v[92:93]
	v_add_f32_e32 v74, 1.0, v101
	v_pk_add_f32 v[88:89], v[86:87], v[84:85]
	v_add_f32_e32 v72, -1.0, v74
	v_pk_add_f32 v[86:87], v[88:89], v[86:87] neg_lo:[0,1] neg_hi:[0,1]
	v_sub_f32_e32 v73, v72, v74
	v_pk_add_f32 v[84:85], v[84:85], v[86:87] neg_lo:[0,1] neg_hi:[0,1]
	v_add_f32_e32 v73, 1.0, v73
	v_pk_add_f32 v[82:83], v[82:83], v[84:85]
	v_mul_f32_e64 v84, |v66|, s62
	v_pk_add_f32 v[82:83], v[88:89], v[82:83]
	v_exp_f32_e32 v100, v84
	v_cndmask_b32_e32 v82, v200, v82, vcc
	v_cmp_neq_f32_e32 vcc, s64, v123
	v_sub_f32_e32 v72, v101, v72
	v_add_f32_e32 v84, 1.0, v100
	v_cndmask_b32_e32 v83, v200, v83, vcc
	v_cmp_ngt_f32_e32 vcc, -1.0, v123
	v_frexp_mant_f32_e32 v86, v84
	v_add_f32_e32 v75, v72, v73
	v_cndmask_b32_e32 v83, v201, v83, vcc
	v_cmp_ngt_f32_e32 vcc, -1.0, v122
	v_frexp_mant_f32_e32 v76, v74
	v_cvt_f64_f32_e32 v[72:73], v74
	v_cndmask_b32_e32 v82, v201, v82, vcc
	v_cmp_neq_f32_e32 vcc, -1.0, v122
	v_frexp_exp_i32_f64_e32 v72, v[72:73]
	v_min_f32_e32 v66, 0, v66
	v_cndmask_b32_e32 v82, v202, v82, vcc
	v_cmp_neq_f32_e32 vcc, -1.0, v123
	s_nop 1
	v_cndmask_b32_e32 v83, v202, v83, vcc
	v_cmp_lt_f32_e64 vcc, |v123|, s65
	s_nop 1
	v_cndmask_b32_e32 v83, v83, v123, vcc
	v_cmp_lt_f32_e64 vcc, |v122|, s65
	s_nop 1
	v_cndmask_b32_e32 v82, v82, v122, vcc
	v_pk_add_f32 v[64:65], v[64:65], v[82:83] neg_lo:[0,1] neg_hi:[0,1]
	v_add_f32_e32 v82, -1.0, v84
	v_sub_f32_e32 v83, v82, v84
	v_add_f32_e32 v83, 1.0, v83
	v_sub_f32_e32 v82, v100, v82
	v_add_f32_e32 v85, v82, v83
	v_cvt_f64_f32_e32 v[82:83], v84
	v_frexp_exp_i32_f64_e32 v82, v[82:83]
	v_cmp_gt_f32_e32 vcc, s63, v86
	s_nop 1
	v_subbrev_co_u32_e32 v94, vcc, 0, v82, vcc
	v_cmp_gt_f32_e32 vcc, s63, v76
	v_sub_u32_e32 v83, 0, v94
	v_ldexp_f32 v82, v84, v83
	v_subbrev_co_u32_e32 v95, vcc, 0, v72, vcc
	v_sub_u32_e32 v72, 0, v95
	v_ldexp_f32 v84, v85, v83
	v_ldexp_f32 v83, v74, v72
	v_ldexp_f32 v85, v75, v72
	v_pk_add_f32 v[72:73], v[82:83], 1.0 op_sel_hi:[1,0]
	v_pk_add_f32 v[86:87], v[82:83], -1.0 op_sel_hi:[1,0]
	v_pk_add_f32 v[74:75], v[72:73], -1.0 op_sel_hi:[1,0]
	v_pk_add_f32 v[88:89], v[86:87], 1.0 op_sel_hi:[1,0]
	v_pk_add_f32 v[74:75], v[82:83], v[74:75] neg_lo:[0,1] neg_hi:[0,1]
	v_pk_add_f32 v[82:83], v[82:83], v[88:89] neg_lo:[0,1] neg_hi:[0,1]
	v_pk_add_f32 v[74:75], v[84:85], v[74:75]
	v_pk_add_f32 v[82:83], v[84:85], v[82:83]
	v_pk_add_f32 v[76:77], v[72:73], v[74:75]
	v_pk_add_f32 v[84:85], v[86:87], v[82:83]
	v_rcp_f32_e32 v78, v76
	v_rcp_f32_e32 v79, v77
	v_pk_add_f32 v[72:73], v[76:77], v[72:73] neg_lo:[0,1] neg_hi:[0,1]
	v_pk_add_f32 v[86:87], v[84:85], v[86:87] neg_lo:[0,1] neg_hi:[0,1]
	v_pk_add_f32 v[72:73], v[74:75], v[72:73] neg_lo:[0,1] neg_hi:[0,1]
	v_pk_mul_f32 v[74:75], v[84:85], v[78:79]
	v_pk_add_f32 v[82:83], v[82:83], v[86:87] neg_lo:[0,1] neg_hi:[0,1]
	v_pk_mul_f32 v[86:87], v[76:77], v[74:75]
	v_cmp_neq_f32_e32 vcc, s64, v100
	v_pk_fma_f32 v[88:89], v[74:75], v[76:77], v[86:87] neg_lo:[0,0,1] neg_hi:[0,0,1]
	s_nop 0
	v_pk_fma_f32 v[88:89], v[74:75], v[72:73], v[88:89]
	s_nop 0
	v_pk_add_f32 v[90:91], v[86:87], v[88:89]
	s_nop 0
	v_pk_add_f32 v[92:93], v[84:85], v[90:91] neg_lo:[0,1] neg_hi:[0,1]
	v_pk_add_f32 v[86:87], v[90:91], v[86:87] neg_lo:[0,1] neg_hi:[0,1]
	v_pk_add_f32 v[84:85], v[84:85], v[92:93] neg_lo:[0,1] neg_hi:[0,1]
	s_nop 0
	v_pk_add_f32 v[84:85], v[84:85], v[90:91] neg_lo:[0,1] neg_hi:[0,1]
	s_nop 0
	v_pk_add_f32 v[82:83], v[82:83], v[84:85]
	v_pk_add_f32 v[84:85], v[86:87], v[88:89] neg_lo:[0,1] neg_hi:[0,1]
	s_nop 0
	v_pk_add_f32 v[82:83], v[84:85], v[82:83]
	s_nop 0
	v_pk_add_f32 v[84:85], v[92:93], v[82:83]
	s_nop 0
	v_pk_mul_f32 v[86:87], v[78:79], v[84:85]
	s_nop 0
	v_pk_mul_f32 v[88:89], v[76:77], v[86:87]
	s_nop 0
	v_pk_fma_f32 v[76:77], v[86:87], v[76:77], v[88:89] neg_lo:[0,0,1] neg_hi:[0,0,1]
	s_nop 0
	v_pk_fma_f32 v[72:73], v[86:87], v[72:73], v[76:77]
	v_pk_add_f32 v[76:77], v[92:93], v[84:85] neg_lo:[0,1] neg_hi:[0,1]
	s_nop 0
	v_pk_add_f32 v[76:77], v[82:83], v[76:77]
	v_pk_add_f32 v[82:83], v[88:89], v[72:73]
	s_nop 0
	v_pk_add_f32 v[90:91], v[84:85], v[82:83] neg_lo:[0,1] neg_hi:[0,1]
	v_pk_add_f32 v[88:89], v[82:83], v[88:89] neg_lo:[0,1] neg_hi:[0,1]
	v_pk_add_f32 v[84:85], v[84:85], v[90:91] neg_lo:[0,1] neg_hi:[0,1]
	v_pk_add_f32 v[72:73], v[88:89], v[72:73] neg_lo:[0,1] neg_hi:[0,1]
	v_pk_add_f32 v[82:83], v[84:85], v[82:83] neg_lo:[0,1] neg_hi:[0,1]
	s_nop 0
	v_pk_add_f32 v[76:77], v[76:77], v[82:83]
	v_cvt_f32_i32_e32 v83, v95
	v_pk_add_f32 v[72:73], v[72:73], v[76:77]
	v_pk_add_f32 v[76:77], v[74:75], v[86:87]
	v_pk_add_f32 v[72:73], v[90:91], v[72:73]
	v_pk_add_f32 v[74:75], v[76:77], v[74:75] neg_lo:[0,1] neg_hi:[0,1]
	v_pk_mul_f32 v[72:73], v[78:79], v[72:73]
	v_pk_add_f32 v[74:75], v[86:87], v[74:75] neg_lo:[0,1] neg_hi:[0,1]
	v_cvt_f32_i32_e32 v82, v94
	v_pk_add_f32 v[72:73], v[74:75], v[72:73]
	s_nop 0
	v_pk_add_f32 v[74:75], v[76:77], v[72:73]
	s_nop 0
	v_pk_mul_f32 v[78:79], v[74:75], v[74:75]
	v_pk_add_f32 v[76:77], v[74:75], v[76:77] neg_lo:[0,1] neg_hi:[0,1]
	v_pk_fma_f32 v[80:81], v[78:79], s[46:47], v[80:81] op_sel_hi:[1,0,0]
	v_pk_add_f32 v[72:73], v[72:73], v[76:77] neg_lo:[0,1] neg_hi:[0,1]
	v_ldexp_f32 v76, v74, 1
	v_pk_fma_f32 v[80:81], v[78:79], v[80:81], s[48:49] op_sel_hi:[1,1,0]
	v_ldexp_f32 v77, v75, 1
	v_pk_mul_f32 v[74:75], v[74:75], v[78:79]
	v_pk_mul_f32 v[78:79], v[82:83], s[50:51] op_sel_hi:[1,0]
	v_pk_mul_f32 v[74:75], v[74:75], v[80:81]
	v_pk_fma_f32 v[86:87], v[82:83], s[50:51], v[78:79] op_sel_hi:[1,0,1] neg_lo:[0,0,1] neg_hi:[0,0,1]
	v_pk_add_f32 v[80:81], v[76:77], v[74:75]
	v_ldexp_f32 v85, v73, 1
	v_pk_add_f32 v[76:77], v[80:81], v[76:77] neg_lo:[0,1] neg_hi:[0,1]
	v_pk_fma_f32 v[82:83], v[82:83], s[52:53], v[86:87] op_sel_hi:[1,0,1]
	v_pk_add_f32 v[74:75], v[74:75], v[76:77] neg_lo:[0,1] neg_hi:[0,1]
	v_ldexp_f32 v72, v72, 1
	v_mov_b32_e32 v76, v78
	v_mov_b32_e32 v77, v75
	v_mov_b32_e32 v84, v82
	v_mov_b32_e32 v73, v85
	v_pk_add_f32 v[76:77], v[76:77], v[84:85]
	v_pk_add_f32 v[84:85], v[72:73], v[74:75]
	v_mov_b32_e32 v75, v81
	v_mov_b32_e32 v73, v85
	v_pk_add_f32 v[86:87], v[78:79], v[82:83]
	v_pk_add_f32 v[72:73], v[72:73], v[74:75]
	v_pk_add_f32 v[74:75], v[80:81], v[84:85]
	v_mov_b32_e32 v96, v80
	v_pk_add_f32 v[88:89], v[86:87], v[74:75]
	v_mov_b32_e32 v94, v74
	v_mov_b32_e32 v95, v89
	v_mov_b32_e32 v97, v87
	v_pk_add_f32 v[94:95], v[94:95], v[96:97] neg_lo:[0,1] neg_hi:[0,1]
	v_mov_b32_e32 v90, v88
	v_mov_b32_e32 v91, v87
	v_mov_b32_e32 v92, v86
	v_mov_b32_e32 v93, v79
	v_mov_b32_e32 v96, v86
	v_mov_b32_e32 v97, v89
	v_mov_b32_e32 v79, v95
	v_pk_add_f32 v[90:91], v[90:91], v[92:93] neg_lo:[0,1] neg_hi:[0,1]
	v_mov_b32_e32 v92, v74
	v_mov_b32_e32 v93, v83
	v_pk_add_f32 v[78:79], v[96:97], v[78:79] neg_lo:[0,1] neg_hi:[0,1]
	v_pk_add_f32 v[92:93], v[92:93], v[90:91] neg_lo:[0,1] neg_hi:[0,1]
	v_mov_b32_e32 v96, v78
	v_mov_b32_e32 v97, v91
	v_mov_b32_e32 v98, v88
	v_mov_b32_e32 v99, v75
	v_mov_b32_e32 v91, v81
	v_pk_add_f32 v[96:97], v[82:83], v[96:97] neg_lo:[0,1] neg_hi:[0,1]
	v_pk_add_f32 v[90:91], v[98:99], v[90:91] neg_lo:[0,1] neg_hi:[0,1]
	v_mov_b32_e32 v83, v87
	v_pk_add_f32 v[76:77], v[76:77], v[90:91] neg_lo:[0,1] neg_hi:[0,1]
	v_pk_add_f32 v[78:79], v[82:83], v[78:79] neg_lo:[0,1] neg_hi:[0,1]
	v_pk_add_f32 v[72:73], v[72:73], v[94:95] neg_lo:[0,1] neg_hi:[0,1]
	v_pk_add_f32 v[74:75], v[74:75], v[80:81] neg_lo:[0,1] neg_hi:[0,1]
	v_pk_add_f32 v[80:81], v[72:73], v[78:79]
	v_mov_b32_e32 v79, v93
	v_mov_b32_e32 v73, v77
	v_pk_add_f32 v[82:83], v[92:93], v[76:77]
	v_pk_add_f32 v[72:73], v[78:79], v[72:73]
	v_mov_b32_e32 v76, v80
	v_pk_add_f32 v[72:73], v[72:73], v[96:97] neg_lo:[0,1] neg_hi:[0,1]
	v_mov_b32_e32 v77, v83
	v_pk_add_f32 v[74:75], v[84:85], v[74:75] neg_lo:[0,1] neg_hi:[0,1]
	v_pk_add_f32 v[76:77], v[76:77], v[72:73] neg_lo:[0,1] neg_hi:[0,1]
	v_pk_add_f32 v[72:73], v[74:75], v[72:73] neg_lo:[0,1] neg_hi:[0,1]
	v_pk_add_f32 v[76:77], v[78:79], v[76:77] neg_lo:[0,1] neg_hi:[0,1]
	v_pk_add_f32 v[74:75], v[82:83], v[80:81]
	v_pk_add_f32 v[72:73], v[72:73], v[76:77]
	v_pk_add_f32 v[76:77], v[88:89], v[74:75]
	s_nop 0
	v_pk_add_f32 v[78:79], v[76:77], v[88:89] neg_lo:[0,1] neg_hi:[0,1]
	s_nop 0
	v_pk_add_f32 v[74:75], v[74:75], v[78:79] neg_lo:[0,1] neg_hi:[0,1]
	s_nop 0
	v_pk_add_f32 v[72:73], v[72:73], v[74:75]
	s_nop 0
	v_pk_add_f32 v[72:73], v[76:77], v[72:73]
	s_nop 0
	v_cndmask_b32_e32 v72, v200, v72, vcc
	v_cmp_neq_f32_e32 vcc, s64, v101
	s_nop 1
	v_cndmask_b32_e32 v73, v200, v73, vcc
	v_cmp_ngt_f32_e32 vcc, -1.0, v101
	s_nop 1
	v_cndmask_b32_e32 v73, v201, v73, vcc
	v_cmp_ngt_f32_e32 vcc, -1.0, v100
	s_nop 1
	v_cndmask_b32_e32 v72, v201, v72, vcc
	v_cmp_neq_f32_e32 vcc, -1.0, v100
	s_nop 1
	v_cndmask_b32_e32 v72, v202, v72, vcc
	v_cmp_neq_f32_e32 vcc, -1.0, v101
	s_nop 1
	v_cndmask_b32_e32 v73, v202, v73, vcc
	v_cmp_lt_f32_e64 vcc, |v101|, s65
	s_nop 1
	v_cndmask_b32_e32 v73, v73, v101, vcc
	v_cmp_lt_f32_e64 vcc, |v100|, s65
	s_nop 1
	v_cndmask_b32_e32 v72, v72, v100, vcc
	v_pk_add_f32 v[66:67], v[66:67], v[72:73] neg_lo:[0,1] neg_hi:[0,1]
	global_store_dwordx4 v129, v[68:71], s[10:11]
	global_store_dwordx4 v129, v[64:67], s[10:11] offset:16
	s_branch .LBB0_261
